# stack + counted lgkmcnt waits per MFMA in the attention P.V sections
# baseline (speedup 1.0000x reference)
; template <int D0> __device__ __forceinline__ void pv_one(f32x16& od, int vb, bf16x8 pa0, bf16x8 pa1, bf16x8 pa2, bf16x8 pa3) {
;     const s16x4 l0 = tr_read<v_rd_off(D0, 0, 0)>(vb), h0 = tr_read<v_rd_off(D0, 0, 1)>(vb), l1 = tr_read<v_rd_off(D0, 1, 0)>(vb), h1 = tr_read<v_rd_off(D0, 1, 1)>(vb);
;     const s16x4 l2 = tr_read<v_rd_off(D0, 2, 0)>(vb), h2 = tr_read<v_rd_off(D0, 2, 1)>(vb), l3 = tr_read<v_rd_off(D0, 3, 0)>(vb), h3 = tr_read<v_rd_off(D0, 3, 1)>(vb);
;     asm volatile("s_waitcnt lgkmcnt(0)" ::: "memory"); SBAR();
;     ...
;     od = __builtin_amdgcn_mfma_f32_32x32x16_bf16(pa0, PK(l0, h0), od, 0, 0, 0);
;     od = __builtin_amdgcn_mfma_f32_32x32x16_bf16(pa1, PK(l1, h1), od, 0, 0, 0);
;     od = __builtin_amdgcn_mfma_f32_32x32x16_bf16(pa2, PK(l2, h2), od, 0, 0, 0);
;     od = __builtin_amdgcn_mfma_f32_32x32x16_bf16(pa3, PK(l3, h3), od, 0, 0, 0);
;     ...
; }
; __device__ __forceinline__ void pv_d0(f32x16* o, int vb, bf16x8 pa0, bf16x8 pa1, bf16x8 pa2, bf16x8 pa3) {
;     pv_one<0>(o[0], vb, pa0, pa1, pa2, pa3); pv_one<1>(o[1], vb, pa0, pa1, pa2, pa3); pv_one<2>(o[2], vb, pa0, pa1, pa2, pa3); pv_one<3>(o[3], vb, pa0, pa1, pa2, pa3);
; }
; __device__ __forceinline__ void partialSM(f32x16& p0, f32x16& p1, float& m_reg, float& mn, float& alpha, const float C, const float thr_raw) {
;     float pmax = p0[0];
; #pragma unroll
;     for (int r = 1; r < 16; ++r) pmax = fmaxf(pmax, p0[r]);
; #pragma unroll
;     for (int r = 0; r < 16; ++r) pmax = fmaxf(pmax, p1[r]);
;     { auto rr = __builtin_amdgcn_permlane32_swap(__float_as_uint(pmax), __float_as_uint(pmax), false, false);
;       pmax = fmaxf(__uint_as_float(rr[0]), __uint_as_float(rr[1])); }
;     if (__builtin_expect(__all(pmax - m_reg <= thr_raw), 1)) { mn = m_reg; alpha = 1.f; }
;     else { mn = fmaxf(m_reg, pmax); alpha = __builtin_amdgcn_exp2f((m_reg - mn) * C); m_reg = mn; }
;     const float mnC = -mn * C;
; #pragma unroll
;     for (int r = 0; r < 16; ++r) p0[r] = fmaf(p0[r], C, mnC);
; #pragma unroll
;     for (int r = 0; r < 16; ++r) p1[r] = fmaf(p1[r], C, mnC);
; #pragma unroll
;     for (int r = 0; r < 16; ++r) p0[r] = __builtin_amdgcn_exp2f(p0[r]);
; }
; __device__ __forceinline__ void finishSM(f32x16& p0, f32x16& p1, float alpha, float& l_reg, bf16x8& pa0, bf16x8& pa1, bf16x8& pa2, bf16x8& pa3) {
; #pragma unroll
;     for (int r = 0; r < 16; ++r) p1[r] = __builtin_amdgcn_exp2f(p1[r]);
.LBB0_3449:
	s_mov_b32 s24, s25
	s_lshl_b32 s25, s7, 14
	s_add_i32 s14, s25, 0
	v_add_u32_e32 v68, s14, v169
	ds_read_b128 v[64:67], v68 offset:49152
	ds_read_b128 v[68:71], v68 offset:57344
	v_add_u32_e32 v158, s14, v171
	ds_read_b128 v[220:223], v158 offset:49152
	ds_read_b128 v[228:231], v158 offset:57344
	v_add_u32_e32 v158, s14, v170
	ds_read_b128 v[236:239], v158 offset:49152
	ds_read_b128 v[240:243], v158 offset:57344
	s_waitcnt lgkmcnt(4)
	v_mfma_f32_32x32x16_bf16 v[80:95], v[64:67], v[124:127], 0
	v_exp_f32_e32 v152, v152
	v_exp_f32_e32 v153, v153
	v_exp_f32_e32 v150, v150
	v_exp_f32_e32 v151, v151
	v_exp_f32_e32 v148, v148
	v_exp_f32_e32 v149, v149
	v_exp_f32_e32 v194, v147
	v_mfma_f32_32x32x16_bf16 v[64:79], v[68:71], v[124:127], 0
	v_exp_f32_e32 v195, v144
	v_exp_f32_e32 v227, v129
	v_cvt_pk_bf16_f32 v129, v207, v210
	v_cvt_pk_bf16_f32 v144, v196, v198
	v_cvt_pk_bf16_f32 v147, v150, v151
	s_waitcnt lgkmcnt(2)
	v_mfma_f32_32x32x16_bf16 v[80:95], v[220:223], v[120:123], v[80:95]
	v_mfma_f32_32x32x16_bf16 v[64:79], v[228:231], v[120:123], v[64:79]
	v_add_u32_e32 v158, s14, v168
	ds_read_b128 v[220:223], v158 offset:49152
	ds_read_b128 v[228:231], v158 offset:57344
	s_waitcnt lgkmcnt(2)
	v_mfma_f32_32x32x16_bf16 v[80:95], v[236:239], v[116:119], v[80:95]
	v_mfma_f32_32x32x16_bf16 v[64:79], v[240:243], v[116:119], v[64:79]
	v_add_u32_e32 v158, s14, v167
	ds_read_b128 v[236:239], v158 offset:49152
	ds_read_b128 v[240:243], v158 offset:57344
	s_waitcnt lgkmcnt(2)
	v_mfma_f32_32x32x16_bf16 v[80:95], v[220:223], v[112:115], v[80:95]
	v_mfma_f32_32x32x16_bf16 v[64:79], v[228:231], v[112:115], v[64:79]
	v_add_u32_e32 v158, s14, v163
	ds_read_b128 v[220:223], v158 offset:49152
	ds_read_b128 v[228:231], v158 offset:57344
	s_waitcnt lgkmcnt(2)
	v_mfma_f32_32x32x16_bf16 v[80:95], v[236:239], v[108:111], v[80:95]
	v_mfma_f32_32x32x16_bf16 v[64:79], v[240:243], v[108:111], v[64:79]
	v_add_u32_e32 v158, s14, v164
	ds_read_b128 v[236:239], v158 offset:49152
	ds_read_b128 v[240:243], v158 offset:57344
	s_waitcnt lgkmcnt(2)
	v_mfma_f32_32x32x16_bf16 v[80:95], v[220:223], v[104:107], v[80:95]
	v_mfma_f32_32x32x16_bf16 v[64:79], v[228:231], v[104:107], v[64:79]
	v_add_u32_e32 v158, s14, v165
	ds_read_b128 v[220:223], v158 offset:49152
	ds_read_b128 v[228:231], v158 offset:57344
	s_waitcnt lgkmcnt(2)
	v_mfma_f32_32x32x16_bf16 v[80:95], v[236:239], v[100:103], v[80:95]
	v_mfma_f32_32x32x16_bf16 v[64:79], v[240:243], v[100:103], v[64:79]
	v_exp_f32_e32 v158, v146
	v_cvt_pk_bf16_f32 v146, v152, v153
	s_waitcnt lgkmcnt(0)
	v_mfma_f32_32x32x16_bf16 v[80:95], v[220:223], v[96:99], v[80:95]
	v_exp_f32_e32 v223, v128
	v_add_f32_e32 v128, 0, v206
	v_add_f32_e32 v128, v209, v128
	v_add_f32_e32 v128, v207, v128
	v_add_f32_e32 v128, v210, v128
	v_add_f32_e32 v128, v208, v128
	v_add_f32_e32 v128, v211, v128
	v_add_f32_e32 v128, v204, v128
	v_add_f32_e32 v128, v205, v128
	v_add_f32_e32 v128, v200, v128
	v_add_f32_e32 v128, v202, v128
	v_add_f32_e32 v128, v201, v128
	v_add_f32_e32 v128, v203, v128
	v_add_f32_e32 v128, v196, v128
	v_add_f32_e32 v128, v198, v128
	v_add_f32_e32 v128, v197, v128
	v_add_f32_e32 v128, v199, v128
	v_add_f32_e32 v128, v152, v128
	v_add_f32_e32 v128, v153, v128
	v_add_f32_e32 v128, v150, v128
	v_add_f32_e32 v128, v151, v128
	v_add_f32_e32 v128, v148, v128
	v_exp_f32_e32 v220, v145
	v_add_f32_e32 v128, v149, v128
	v_exp_f32_e32 v221, v130
	v_add_f32_e32 v128, v158, v128
	v_exp_f32_e32 v222, v131
	v_add_f32_e32 v128, v194, v128
	v_add_f32_e32 v128, v195, v128
	v_add_f32_e32 v128, v220, v128
	v_mfma_f32_32x32x16_bf16 v[64:79], v[228:231], v[96:99], v[64:79]
	v_exp_f32_e32 v228, v142
	v_add_f32_e32 v128, v221, v128
	v_exp_f32_e32 v229, v143
	v_add_f32_e32 v128, v222, v128
	v_add_f32_e32 v128, v223, v128
	v_add_f32_e32 v128, v227, v128
	v_add_f32_e32 v128, v228, v128
	v_add_f32_e32 v174, v229, v128
	v_mov_b32_e32 v175, v174
	v_cvt_pk_bf16_f32 v128, v206, v209
	v_cvt_pk_bf16_f32 v130, v208, v211
	s_nop 1
	v_permlane32_swap_b32_e32 v174, v175
	v_cvt_pk_bf16_f32 v131, v204, v205
	v_permlane32_swap_b32_e32 v128, v130
	v_cvt_pk_bf16_f32 v142, v200, v202
	v_cvt_pk_bf16_f32 v143, v201, v203
	v_cvt_pk_bf16_f32 v145, v197, v199
	v_cvt_pk_bf16_f32 v148, v148, v149
	v_cvt_pk_bf16_f32 v149, v158, v194
	v_cvt_pk_bf16_f32 v150, v195, v220
	v_cvt_pk_bf16_f32 v151, v221, v222
	v_cvt_pk_bf16_f32 v152, v223, v227
	v_cvt_pk_bf16_f32 v153, v228, v229
	v_permlane32_swap_b32_e32 v129, v131
	v_permlane32_swap_b32_e32 v142, v144
	v_permlane32_swap_b32_e32 v143, v145
	v_permlane32_swap_b32_e32 v146, v148
	v_permlane32_swap_b32_e32 v147, v149
	v_permlane32_swap_b32_e32 v150, v152
	v_permlane32_swap_b32_e32 v151, v153
	s_lshl_b32 s26, s44, 14
	v_add_u32_e32 v158, s26, v159
	ds_read_b64_tr_b16 v[194:195], v158 offset:0
	ds_read_b64_tr_b16 v[196:197], v158 offset:0x800
	ds_read_b64_tr_b16 v[198:199], v158 offset:0x1000
	ds_read_b64_tr_b16 v[200:201], v158 offset:0x1800
	ds_read_b64_tr_b16 v[202:203], v158 offset:0x2000
	ds_read_b64_tr_b16 v[204:205], v158 offset:0x2800
	ds_read_b64_tr_b16 v[206:207], v158 offset:0x3000
	ds_read_b64_tr_b16 v[208:209], v158 offset:0x3800
	s_nop 0
	s_waitcnt lgkmcnt(6)
; #define SBAR() __builtin_amdgcn_sched_barrier(0)
; template <int D0> __device__ __forceinline__ void pv_one(f32x16& od, int vb, bf16x8 pa0, bf16x8 pa1, bf16x8 pa2, bf16x8 pa3) {
;     const s16x4 l0 = tr_read<v_rd_off(D0, 0, 0)>(vb), h0 = tr_read<v_rd_off(D0, 0, 1)>(vb), l1 = tr_read<v_rd_off(D0, 1, 0)>(vb), h1 = tr_read<v_rd_off(D0, 1, 1)>(vb);
;     const s16x4 l2 = tr_read<v_rd_off(D0, 2, 0)>(vb), h2 = tr_read<v_rd_off(D0, 2, 1)>(vb), l3 = tr_read<v_rd_off(D0, 3, 0)>(vb), h3 = tr_read<v_rd_off(D0, 3, 1)>(vb);
;     asm volatile("s_waitcnt lgkmcnt(0)" ::: "memory"); SBAR();
;     ...
;     od = __builtin_amdgcn_mfma_f32_32x32x16_bf16(pa0, PK(l0, h0), od, 0, 0, 0);
;     od = __builtin_amdgcn_mfma_f32_32x32x16_bf16(pa1, PK(l1, h1), od, 0, 0, 0);
;     od = __builtin_amdgcn_mfma_f32_32x32x16_bf16(pa2, PK(l2, h2), od, 0, 0, 0);
;     od = __builtin_amdgcn_mfma_f32_32x32x16_bf16(pa3, PK(l3, h3), od, 0, 0, 0);
;     ...
; }
; __device__ __forceinline__ void pv_d0(f32x16* o, int vb, bf16x8 pa0, bf16x8 pa1, bf16x8 pa2, bf16x8 pa3) {
;     pv_one<0>(o[0], vb, pa0, pa1, pa2, pa3); pv_one<1>(o[1], vb, pa0, pa1, pa2, pa3); pv_one<2>(o[2], vb, pa0, pa1, pa2, pa3); pv_one<3>(o[3], vb, pa0, pa1, pa2, pa3);
; }
; __device__ __forceinline__ void partialSM(f32x16& p0, f32x16& p1, float& m_reg, float& mn, float& alpha, const float C, const float thr_raw) {
;     float pmax = p0[0];
; #pragma unroll
;     for (int r = 1; r < 16; ++r) pmax = fmaxf(pmax, p0[r]);
; #pragma unroll
;     for (int r = 0; r < 16; ++r) pmax = fmaxf(pmax, p1[r]);
;     { auto rr = __builtin_amdgcn_permlane32_swap(__float_as_uint(pmax), __float_as_uint(pmax), false, false);
;       pmax = fmaxf(__uint_as_float(rr[0]), __uint_as_float(rr[1])); }
;     if (__builtin_expect(__all(pmax - m_reg <= thr_raw), 1)) { mn = m_reg; alpha = 1.f; }
	v_mfma_f32_32x32x16_bf16 v[0:15], v[128:131], v[194:197], v[0:15]
	ds_read_b64_tr_b16 v[194:195], v158 offset:0x200
	ds_read_b64_tr_b16 v[196:197], v158 offset:0xa00
	s_waitcnt lgkmcnt(6)
	v_mfma_f32_32x32x16_bf16 v[0:15], v[142:145], v[198:201], v[0:15]
	ds_read_b64_tr_b16 v[198:199], v158 offset:0x1200
	ds_read_b64_tr_b16 v[200:201], v158 offset:0x1a00
	s_waitcnt lgkmcnt(6)
	v_mfma_f32_32x32x16_bf16 v[0:15], v[146:149], v[202:205], v[0:15]
	ds_read_b64_tr_b16 v[202:203], v158 offset:0x2200
	ds_read_b64_tr_b16 v[204:205], v158 offset:0x2a00
	s_waitcnt lgkmcnt(6)
	v_mfma_f32_32x32x16_bf16 v[0:15], v[150:153], v[206:209], v[0:15]
	ds_read_b64_tr_b16 v[206:207], v158 offset:0x3200
	ds_read_b64_tr_b16 v[208:209], v158 offset:0x3a00
	s_waitcnt lgkmcnt(6)
	v_mfma_f32_32x32x16_bf16 v[48:63], v[128:131], v[194:197], v[48:63]
	ds_read_b64_tr_b16 v[194:195], v158 offset:0x400
	ds_read_b64_tr_b16 v[196:197], v158 offset:0xc00
	s_waitcnt lgkmcnt(6)
	v_mfma_f32_32x32x16_bf16 v[48:63], v[142:145], v[198:201], v[48:63]
	ds_read_b64_tr_b16 v[198:199], v158 offset:0x1400
	ds_read_b64_tr_b16 v[200:201], v158 offset:0x1c00
	s_waitcnt lgkmcnt(6)
	v_mfma_f32_32x32x16_bf16 v[48:63], v[146:149], v[202:205], v[48:63]
	ds_read_b64_tr_b16 v[202:203], v158 offset:0x2400
	ds_read_b64_tr_b16 v[204:205], v158 offset:0x2c00
	s_waitcnt lgkmcnt(6)
	v_mfma_f32_32x32x16_bf16 v[48:63], v[150:153], v[206:209], v[48:63]
	ds_read_b64_tr_b16 v[206:207], v158 offset:0x3400
	ds_read_b64_tr_b16 v[208:209], v158 offset:0x3c00
	s_waitcnt lgkmcnt(6)
	v_mfma_f32_32x32x16_bf16 v[32:47], v[128:131], v[194:197], v[32:47]
	ds_read_b64_tr_b16 v[194:195], v158 offset:0x600
	ds_read_b64_tr_b16 v[196:197], v158 offset:0xe00
	s_waitcnt lgkmcnt(6)
	v_mfma_f32_32x32x16_bf16 v[32:47], v[142:145], v[198:201], v[32:47]
	ds_read_b64_tr_b16 v[198:199], v158 offset:0x1600
	ds_read_b64_tr_b16 v[200:201], v158 offset:0x1e00
	s_waitcnt lgkmcnt(6)
	v_mfma_f32_32x32x16_bf16 v[32:47], v[146:149], v[202:205], v[32:47]
	ds_read_b64_tr_b16 v[202:203], v158 offset:0x2600
	ds_read_b64_tr_b16 v[204:205], v158 offset:0x2e00
	s_waitcnt lgkmcnt(6)
	v_mfma_f32_32x32x16_bf16 v[32:47], v[150:153], v[206:209], v[32:47]
	ds_read_b64_tr_b16 v[206:207], v158 offset:0x3600
	ds_read_b64_tr_b16 v[208:209], v158 offset:0x3e00
	s_waitcnt lgkmcnt(6)
	v_mfma_f32_32x32x16_bf16 v[16:31], v[128:131], v[194:197], v[16:31]
	v_max_f32_e32 v128, v81, v81
	v_max_f32_e32 v129, v80, v80
	v_max_f32_e32 v128, v129, v128
	v_max3_f32 v128, v128, v82, v83
	v_max3_f32 v128, v128, v84, v85
	v_max3_f32 v128, v128, v86, v87
	v_max3_f32 v128, v128, v88, v89
	s_waitcnt lgkmcnt(4)
	v_mfma_f32_32x32x16_bf16 v[16:31], v[142:145], v[198:201], v[16:31]
	v_max3_f32 v128, v128, v90, v91
	v_max3_f32 v128, v128, v92, v93
	v_max3_f32 v128, v128, v94, v95
	v_max3_f32 v128, v128, v64, v65
	v_max3_f32 v128, v128, v66, v67
	v_max3_f32 v128, v128, v68, v69
	v_max3_f32 v128, v128, v70, v71
	s_waitcnt lgkmcnt(2)
	v_mfma_f32_32x32x16_bf16 v[16:31], v[146:149], v[202:205], v[16:31]
	v_max3_f32 v128, v128, v72, v73
	v_max3_f32 v128, v128, v74, v75
	v_max3_f32 v128, v128, v76, v77
	v_max3_f32 v128, v128, v78, v79
	v_mov_b32_e32 v129, v128
	s_nop 1
	v_permlane32_swap_b32_e32 v128, v129
	s_waitcnt lgkmcnt(0)
	v_mfma_f32_32x32x16_bf16 v[16:31], v[150:153], v[206:209], v[16:31]
	v_max_f32_e32 v129, v129, v129
	v_max_f32_e32 v128, v128, v128
	v_max_f32_e32 v128, v128, v129
	v_sub_f32_e32 v129, v128, v172
	v_cmp_ge_f32_e32 vcc, s20, v129
	s_cmp_eq_u64 vcc, exec
	s_waitcnt vmcnt(0)
	s_cselect_b64 s[40:41], -1, 0
	s_add_i32 s14, s22, -1
	v_cmp_lt_u32_e32 vcc, s14, v160
	s_waitcnt vmcnt(0)
	s_barrier
	s_and_saveexec_b64 s[42:43], vcc
	s_cbranch_execz .LBB0_3451
	s_sub_i32 s14, s23, 64
	v_cmp_lt_u32_e32 vcc, s14, v161
	s_nop 1
	v_cndmask_b32_e32 v129, v166, v162, vcc
	v_add_u32_e32 v130, s14, v129
	v_ashrrev_i32_e32 v131, 31, v130
	v_lshlrev_b64 v[130:131], 8, v[130:131]
	v_lshl_add_u64 v[142:143], s[86:87], 0, v[130:131]
	s_add_i32 s14, s6, s26
	v_lshl_add_u64 v[144:145], v[134:135], 1, v[142:143]
	s_mov_b32 m0, s14
	v_lshl_add_u64 v[142:143], v[136:137], 1, v[142:143]
	global_load_lds_dwordx4 v[144:145], off
	s_add_i32 m0, s14, 0x2000
	v_lshl_add_u64 v[130:131], s[84:85], 0, v[130:131]
	global_load_lds_dwordx4 v[142:143], off
	s_add_i32 m0, s14, 0xc000
	v_lshl_add_u64 v[142:143], v[138:139], 1, v[130:131]
	global_load_lds_dwordx4 v[142:143], off
	v_lshl_add_u64 v[130:131], v[140:141], 1, v[130:131]
	s_add_i32 m0, s14, 0xe000
	s_nop 0
	global_load_lds_dwordx4 v[130:131], off

; __device__ __forceinline__ void partialSM(f32x16& p0, f32x16& p1, float& m_reg, float& mn, float& alpha, const float C, const float thr_raw) {
;     ...
;     if (__builtin_expect(__all(pmax - m_reg <= thr_raw), 1)) { mn = m_reg; alpha = 1.f; }
;     else { mn = fmaxf(m_reg, pmax); alpha = __builtin_amdgcn_exp2f((m_reg - mn) * C); m_reg = mn; }
;     const float mnC = -mn * C;
; #pragma unroll
;     for (int r = 0; r < 16; ++r) p0[r] = fmaf(p0[r], C, mnC);
; #pragma unroll
;     for (int r = 0; r < 16; ++r) p1[r] = fmaf(p1[r], C, mnC);
; #pragma unroll
;     for (int r = 0; r < 16; ++r) p0[r] = __builtin_amdgcn_exp2f(p0[r]);
; }
; __device__ __forceinline__ void finishSM(f32x16& p0, f32x16& p1, float alpha, float& l_reg, bf16x8& pa0, bf16x8& pa1, bf16x8& pa2, bf16x8& pa3) {
; #pragma unroll
;     for (int r = 0; r < 16; ++r) p1[r] = __builtin_amdgcn_exp2f(p1[r]);
; template <int DQK> __device__ __forceinline__ void qkt(f32x16& p0, f32x16& p1, const char* Ks, const bf16x8* qr, int r32, int hi) {
;     p0 = f32x16{}; p1 = f32x16{};
; #pragma unroll
;     for (int d0 = 0; d0 < DQK / 16; ++d0) { const int cb = (d0 * 16 + hi * 8) * 2;
;         const bf16x8 b0 = *reinterpret_cast<const bf16x8*>(Ks + kswz<DQK>(r32, cb));
;         const bf16x8 b1 = *reinterpret_cast<const bf16x8*>(Ks + kswz<DQK>(32 + r32, cb));
;         p0 = __builtin_amdgcn_mfma_f32_32x32x16_bf16(b0, qr[d0], p0, 0, 0, 0);
;         p1 = __builtin_amdgcn_mfma_f32_32x32x16_bf16(b1, qr[d0], p1, 0, 0, 0); }
.LBB0_3455:
	v_cndmask_b32_e64 v142, v128, v172, s[40:41]
	v_mul_f32_e32 v194, 0xbe0293ee, v142
	v_fmamk_f32 v80, v80, 0x3e0293ee, v194
	v_exp_f32_e32 v128, v80
	v_fmamk_f32 v81, v81, 0x3e0293ee, v194
	v_fmamk_f32 v82, v82, 0x3e0293ee, v194
	v_fmamk_f32 v83, v83, 0x3e0293ee, v194
	v_fmamk_f32 v84, v84, 0x3e0293ee, v194
	v_fmamk_f32 v85, v85, 0x3e0293ee, v194
	v_fmamk_f32 v86, v86, 0x3e0293ee, v194
	v_fmamk_f32 v87, v87, 0x3e0293ee, v194
	v_fmamk_f32 v88, v88, 0x3e0293ee, v194
	v_fmamk_f32 v89, v89, 0x3e0293ee, v194
	v_fmamk_f32 v90, v90, 0x3e0293ee, v194
	v_fmamk_f32 v91, v91, 0x3e0293ee, v194
	v_fmamk_f32 v92, v92, 0x3e0293ee, v194
	v_fmamk_f32 v93, v93, 0x3e0293ee, v194
	v_fmamk_f32 v94, v94, 0x3e0293ee, v194
	v_fmamk_f32 v95, v95, 0x3e0293ee, v194
	v_fmamk_f32 v204, v64, 0x3e0293ee, v194
	v_fmamk_f32 v205, v65, 0x3e0293ee, v194
	v_fmamk_f32 v206, v66, 0x3e0293ee, v194
	v_fmamk_f32 v207, v67, 0x3e0293ee, v194
	v_fmamk_f32 v208, v68, 0x3e0293ee, v194
	v_fmamk_f32 v197, v69, 0x3e0293ee, v194
	v_fmamk_f32 v198, v70, 0x3e0293ee, v194
	v_fmamk_f32 v199, v71, 0x3e0293ee, v194
	v_fmamk_f32 v200, v72, 0x3e0293ee, v194
	v_fmamk_f32 v201, v73, 0x3e0293ee, v194
	v_fmamk_f32 v202, v74, 0x3e0293ee, v194
	v_fmamk_f32 v203, v75, 0x3e0293ee, v194
	v_fmamk_f32 v196, v76, 0x3e0293ee, v194
	v_exp_f32_e32 v172, v81
	v_exp_f32_e32 v129, v82
	v_exp_f32_e32 v153, v83
	v_exp_f32_e32 v130, v84
	v_exp_f32_e32 v152, v85
	v_exp_f32_e32 v131, v86
	v_exp_f32_e32 v151, v87
	v_exp_f32_e32 v148, v88
	v_exp_f32_e32 v150, v89
	v_exp_f32_e32 v147, v90
	v_exp_f32_e32 v149, v91
	v_exp_f32_e32 v144, v92
	v_exp_f32_e32 v146, v93
	v_exp_f32_e32 v143, v94
	v_exp_f32_e32 v145, v95
	v_fmamk_f32 v209, v77, 0x3e0293ee, v194
	v_fmamk_f32 v210, v78, 0x3e0293ee, v194
	v_fmac_f32_e32 v194, 0x3e0293ee, v79
	s_lshl_b32 s27, s24, 14
	s_add_i32 s14, s27, 0
	v_add_u32_e32 v68, s14, v169
	ds_read_b128 v[64:67], v68 offset:49152
	ds_read_b128 v[68:71], v68 offset:57344
	v_add_u32_e32 v211, s14, v171
	ds_read_b128 v[220:223], v211 offset:49152
	ds_read_b128 v[228:231], v211 offset:57344
	v_add_u32_e32 v211, s14, v170
	ds_read_b128 v[236:239], v211 offset:49152
	ds_read_b128 v[240:243], v211 offset:57344
	s_waitcnt lgkmcnt(4)
	v_mfma_f32_32x32x16_bf16 v[80:95], v[64:67], v[124:127], 0
	v_exp_f32_e32 v204, v204
	v_exp_f32_e32 v205, v205
	v_exp_f32_e32 v206, v206
	v_exp_f32_e32 v207, v207
	v_exp_f32_e32 v208, v208
	v_exp_f32_e32 v197, v197
	v_exp_f32_e32 v198, v198
	v_mfma_f32_32x32x16_bf16 v[64:79], v[68:71], v[124:127], 0
	v_exp_f32_e32 v199, v199
	v_exp_f32_e32 v200, v200
	v_exp_f32_e32 v201, v201
	v_exp_f32_e32 v202, v202
	v_exp_f32_e32 v203, v203
	v_exp_f32_e32 v209, v209
	v_exp_f32_e32 v210, v210
	s_waitcnt lgkmcnt(2)
	v_mfma_f32_32x32x16_bf16 v[80:95], v[220:223], v[120:123], v[80:95]
	v_exp_f32_e32 v194, v194
	v_mfma_f32_32x32x16_bf16 v[64:79], v[228:231], v[120:123], v[64:79]
	v_add_u32_e32 v211, s14, v168
	ds_read_b128 v[220:223], v211 offset:49152
	ds_read_b128 v[228:231], v211 offset:57344
	s_waitcnt lgkmcnt(2)
	v_mfma_f32_32x32x16_bf16 v[80:95], v[236:239], v[116:119], v[80:95]
	v_mfma_f32_32x32x16_bf16 v[64:79], v[240:243], v[116:119], v[64:79]
	v_add_u32_e32 v211, s14, v167
	ds_read_b128 v[236:239], v211 offset:49152
	ds_read_b128 v[240:243], v211 offset:57344
	s_waitcnt lgkmcnt(2)
	v_mfma_f32_32x32x16_bf16 v[80:95], v[220:223], v[112:115], v[80:95]
	v_mfma_f32_32x32x16_bf16 v[64:79], v[228:231], v[112:115], v[64:79]
	v_add_u32_e32 v211, s14, v163
	ds_read_b128 v[220:223], v211 offset:49152
	ds_read_b128 v[228:231], v211 offset:57344
	s_waitcnt lgkmcnt(2)
	v_mfma_f32_32x32x16_bf16 v[80:95], v[236:239], v[108:111], v[80:95]
	v_mfma_f32_32x32x16_bf16 v[64:79], v[240:243], v[108:111], v[64:79]
	v_add_u32_e32 v211, s14, v164
	ds_read_b128 v[236:239], v211 offset:49152
	ds_read_b128 v[240:243], v211 offset:57344
	s_waitcnt lgkmcnt(2)
	v_mfma_f32_32x32x16_bf16 v[80:95], v[220:223], v[104:107], v[80:95]
	v_mfma_f32_32x32x16_bf16 v[64:79], v[228:231], v[104:107], v[64:79]
	v_add_u32_e32 v211, s14, v165
	ds_read_b128 v[220:223], v211 offset:49152
	ds_read_b128 v[228:231], v211 offset:57344
	s_waitcnt lgkmcnt(2)
	v_mfma_f32_32x32x16_bf16 v[80:95], v[236:239], v[100:103], v[80:95]
	v_mfma_f32_32x32x16_bf16 v[64:79], v[240:243], v[100:103], v[64:79]
	v_exp_f32_e32 v211, v196
	v_add_f32_e32 v196, 0, v128
	v_add_f32_e32 v196, v172, v196
	v_add_f32_e32 v196, v129, v196
	v_add_f32_e32 v196, v153, v196
	v_add_f32_e32 v196, v130, v196
	v_add_f32_e32 v196, v152, v196
	v_add_f32_e32 v196, v131, v196
	v_add_f32_e32 v196, v151, v196
	v_add_f32_e32 v196, v148, v196
	v_add_f32_e32 v196, v150, v196
	v_add_f32_e32 v196, v147, v196
	v_add_f32_e32 v196, v149, v196
	v_add_f32_e32 v196, v144, v196
	v_add_f32_e32 v196, v146, v196
	v_add_f32_e32 v196, v143, v196
	v_add_f32_e32 v196, v145, v196
	v_add_f32_e32 v196, v204, v196
	v_add_f32_e32 v196, v205, v196
	v_add_f32_e32 v196, v206, v196
	v_add_f32_e32 v196, v207, v196
	v_add_f32_e32 v196, v208, v196
	v_add_f32_e32 v196, v197, v196
	v_add_f32_e32 v196, v198, v196
	v_add_f32_e32 v196, v199, v196
	v_add_f32_e32 v196, v200, v196
	v_add_f32_e32 v196, v201, v196
	s_waitcnt lgkmcnt(0)
; template <int D0> __device__ __forceinline__ void pv_one(f32x16& od, int vb, bf16x8 pa0, bf16x8 pa1, bf16x8 pa2, bf16x8 pa3) {
;     const s16x4 l0 = tr_read<v_rd_off(D0, 0, 0)>(vb), h0 = tr_read<v_rd_off(D0, 0, 1)>(vb), l1 = tr_read<v_rd_off(D0, 1, 0)>(vb), h1 = tr_read<v_rd_off(D0, 1, 1)>(vb);
;     const s16x4 l2 = tr_read<v_rd_off(D0, 2, 0)>(vb), h2 = tr_read<v_rd_off(D0, 2, 1)>(vb), l3 = tr_read<v_rd_off(D0, 3, 0)>(vb), h3 = tr_read<v_rd_off(D0, 3, 1)>(vb);
;     asm volatile("s_waitcnt lgkmcnt(0)" ::: "memory"); SBAR();
;     ...
;     od = __builtin_amdgcn_mfma_f32_32x32x16_bf16(pa0, PK(l0, h0), od, 0, 0, 0);
;     od = __builtin_amdgcn_mfma_f32_32x32x16_bf16(pa1, PK(l1, h1), od, 0, 0, 0);
;     od = __builtin_amdgcn_mfma_f32_32x32x16_bf16(pa2, PK(l2, h2), od, 0, 0, 0);
;     od = __builtin_amdgcn_mfma_f32_32x32x16_bf16(pa3, PK(l3, h3), od, 0, 0, 0);
;     ...
; }
; __device__ __forceinline__ void pv_d0(f32x16* o, int vb, bf16x8 pa0, bf16x8 pa1, bf16x8 pa2, bf16x8 pa3) {
;     pv_one<0>(o[0], vb, pa0, pa1, pa2, pa3); pv_one<1>(o[1], vb, pa0, pa1, pa2, pa3); pv_one<2>(o[2], vb, pa0, pa1, pa2, pa3); pv_one<3>(o[3], vb, pa0, pa1, pa2, pa3);
; }
; __device__ __forceinline__ void partialSM(f32x16& p0, f32x16& p1, float& m_reg, float& mn, float& alpha, const float C, const float thr_raw) {
;     float pmax = p0[0];
; #pragma unroll
;     for (int r = 1; r < 16; ++r) pmax = fmaxf(pmax, p0[r]);
; #pragma unroll
;     for (int r = 0; r < 16; ++r) pmax = fmaxf(pmax, p1[r]);
;     { auto rr = __builtin_amdgcn_permlane32_swap(__float_as_uint(pmax), __float_as_uint(pmax), false, false);
;       pmax = fmaxf(__uint_as_float(rr[0]), __uint_as_float(rr[1])); }
;     if (__builtin_expect(__all(pmax - m_reg <= thr_raw), 1)) { mn = m_reg; alpha = 1.f; }
;     else { mn = fmaxf(m_reg, pmax); alpha = __builtin_amdgcn_exp2f((m_reg - mn) * C); m_reg = mn; }
;     const float mnC = -mn * C;
; #pragma unroll
;     for (int r = 0; r < 16; ++r) p0[r] = fmaf(p0[r], C, mnC);
; #pragma unroll
;     for (int r = 0; r < 16; ++r) p1[r] = fmaf(p1[r], C, mnC);
; #pragma unroll
;     for (int r = 0; r < 16; ++r) p0[r] = __builtin_amdgcn_exp2f(p0[r]);
; }
; __device__ __forceinline__ void finishSM(f32x16& p0, f32x16& p1, float alpha, float& l_reg, bf16x8& pa0, bf16x8& pa1, bf16x8& pa2, bf16x8& pa3) {
; #pragma unroll
;     for (int r = 0; r < 16; ++r) p1[r] = __builtin_amdgcn_exp2f(p1[r]);
	v_mfma_f32_32x32x16_bf16 v[80:95], v[220:223], v[96:99], v[80:95]
	v_add_f32_e32 v196, v202, v196
	v_add_f32_e32 v196, v203, v196
	v_add_f32_e32 v196, v211, v196
	v_add_f32_e32 v196, v209, v196
	v_add_f32_e32 v196, v210, v196
	v_add_f32_e32 v227, v194, v196
	v_cvt_pk_bf16_f32 v128, v128, v172
	v_mfma_f32_32x32x16_bf16 v[64:79], v[228:231], v[96:99], v[64:79]
	v_mov_b32_e32 v228, v227
	v_cvt_pk_bf16_f32 v130, v130, v152
	s_nop 1
	v_permlane32_swap_b32_e32 v227, v228
	v_cvt_pk_bf16_f32 v129, v129, v153
	v_cvt_pk_bf16_f32 v131, v131, v151
	v_permlane32_swap_b32_e32 v128, v130
	v_cvt_pk_bf16_f32 v148, v148, v150
	v_cvt_pk_bf16_f32 v149, v147, v149
	v_cvt_pk_bf16_f32 v150, v144, v146
	v_cvt_pk_bf16_f32 v151, v143, v145
	v_cvt_pk_bf16_f32 v144, v204, v205
	v_cvt_pk_bf16_f32 v145, v206, v207
	v_cvt_pk_bf16_f32 v146, v208, v197
	v_cvt_pk_bf16_f32 v147, v198, v199
	v_cvt_pk_bf16_f32 v196, v200, v201
	v_cvt_pk_bf16_f32 v197, v202, v203
	v_cvt_pk_bf16_f32 v198, v211, v209
	v_cvt_pk_bf16_f32 v199, v210, v194
	v_permlane32_swap_b32_e32 v129, v131
	v_permlane32_swap_b32_e32 v148, v150
	v_permlane32_swap_b32_e32 v149, v151
	v_permlane32_swap_b32_e32 v144, v146
	v_permlane32_swap_b32_e32 v145, v147
	v_permlane32_swap_b32_e32 v196, v198
	v_permlane32_swap_b32_e32 v197, v199
	v_add_u32_e32 v143, s25, v159
	ds_read_b64_tr_b16 v[200:201], v143 offset:0
	ds_read_b64_tr_b16 v[202:203], v143 offset:0x800
	ds_read_b64_tr_b16 v[204:205], v143 offset:0x1000
	ds_read_b64_tr_b16 v[206:207], v143 offset:0x1800
	ds_read_b64_tr_b16 v[208:209], v143 offset:0x2000
	ds_read_b64_tr_b16 v[210:211], v143 offset:0x2800
	ds_read_b64_tr_b16 v[220:221], v143 offset:0x3000
	ds_read_b64_tr_b16 v[222:223], v143 offset:0x3800
	s_nop 0
	s_waitcnt lgkmcnt(6)
	v_mfma_f32_32x32x16_bf16 v[0:15], v[128:131], v[200:203], v[0:15]
	ds_read_b64_tr_b16 v[200:201], v143 offset:0x200
	ds_read_b64_tr_b16 v[202:203], v143 offset:0xa00
	s_waitcnt lgkmcnt(6)
	v_mfma_f32_32x32x16_bf16 v[0:15], v[148:151], v[204:207], v[0:15]
	ds_read_b64_tr_b16 v[204:205], v143 offset:0x1200
	ds_read_b64_tr_b16 v[206:207], v143 offset:0x1a00
	s_waitcnt lgkmcnt(6)
	v_mfma_f32_32x32x16_bf16 v[0:15], v[144:147], v[208:211], v[0:15]
	ds_read_b64_tr_b16 v[208:209], v143 offset:0x2200
	ds_read_b64_tr_b16 v[210:211], v143 offset:0x2a00
	s_waitcnt lgkmcnt(6)
	v_mfma_f32_32x32x16_bf16 v[0:15], v[196:199], v[220:223], v[0:15]
	ds_read_b64_tr_b16 v[220:221], v143 offset:0x3200
	ds_read_b64_tr_b16 v[222:223], v143 offset:0x3a00
	s_waitcnt lgkmcnt(6)
	v_mfma_f32_32x32x16_bf16 v[48:63], v[128:131], v[200:203], v[48:63]
	ds_read_b64_tr_b16 v[200:201], v143 offset:0x400
	ds_read_b64_tr_b16 v[202:203], v143 offset:0xc00
	s_waitcnt lgkmcnt(6)
	v_mfma_f32_32x32x16_bf16 v[48:63], v[148:151], v[204:207], v[48:63]
	ds_read_b64_tr_b16 v[204:205], v143 offset:0x1400
	ds_read_b64_tr_b16 v[206:207], v143 offset:0x1c00
	s_waitcnt lgkmcnt(6)
	v_mfma_f32_32x32x16_bf16 v[48:63], v[144:147], v[208:211], v[48:63]
	ds_read_b64_tr_b16 v[208:209], v143 offset:0x2400
	ds_read_b64_tr_b16 v[210:211], v143 offset:0x2c00
	s_waitcnt lgkmcnt(6)
	v_mfma_f32_32x32x16_bf16 v[48:63], v[196:199], v[220:223], v[48:63]
	ds_read_b64_tr_b16 v[220:221], v143 offset:0x3400
	ds_read_b64_tr_b16 v[222:223], v143 offset:0x3c00
	s_waitcnt lgkmcnt(6)
	v_mfma_f32_32x32x16_bf16 v[32:47], v[128:131], v[200:203], v[32:47]
	ds_read_b64_tr_b16 v[200:201], v143 offset:0x600
	ds_read_b64_tr_b16 v[202:203], v143 offset:0xe00
	s_waitcnt lgkmcnt(6)
	v_mfma_f32_32x32x16_bf16 v[32:47], v[148:151], v[204:207], v[32:47]
	ds_read_b64_tr_b16 v[204:205], v143 offset:0x1600
	ds_read_b64_tr_b16 v[206:207], v143 offset:0x1e00
	s_waitcnt lgkmcnt(6)
	v_mfma_f32_32x32x16_bf16 v[32:47], v[144:147], v[208:211], v[32:47]
	ds_read_b64_tr_b16 v[208:209], v143 offset:0x2600
	ds_read_b64_tr_b16 v[210:211], v143 offset:0x2e00
	s_waitcnt lgkmcnt(6)
	v_mfma_f32_32x32x16_bf16 v[32:47], v[196:199], v[220:223], v[32:47]
	ds_read_b64_tr_b16 v[220:221], v143 offset:0x3600
	ds_read_b64_tr_b16 v[222:223], v143 offset:0x3e00
	s_waitcnt lgkmcnt(6)
	v_mfma_f32_32x32x16_bf16 v[16:31], v[128:131], v[200:203], v[16:31]
	v_max_f32_e32 v128, v81, v81
	v_max_f32_e32 v129, v80, v80
	v_max_f32_e32 v128, v129, v128
	v_max3_f32 v128, v128, v82, v83
	v_max3_f32 v128, v128, v84, v85
	v_max3_f32 v128, v128, v86, v87
	v_max3_f32 v128, v128, v88, v89
	s_waitcnt lgkmcnt(4)
	v_mfma_f32_32x32x16_bf16 v[16:31], v[148:151], v[204:207], v[16:31]
	v_max3_f32 v128, v128, v90, v91
	v_max3_f32 v128, v128, v92, v93
	v_max3_f32 v128, v128, v94, v95
	v_max3_f32 v128, v128, v64, v65
	v_max3_f32 v128, v128, v66, v67
	v_max3_f32 v128, v128, v68, v69
	v_max3_f32 v128, v128, v70, v71
	s_waitcnt lgkmcnt(2)
	v_mfma_f32_32x32x16_bf16 v[16:31], v[144:147], v[208:211], v[16:31]
	v_max3_f32 v128, v128, v72, v73
	v_max3_f32 v128, v128, v74, v75
	v_max3_f32 v128, v128, v76, v77
	v_max3_f32 v128, v128, v78, v79
	v_mov_b32_e32 v129, v128
	s_nop 1
	v_permlane32_swap_b32_e32 v128, v129
	s_waitcnt lgkmcnt(0)
	v_mfma_f32_32x32x16_bf16 v[16:31], v[196:199], v[220:223], v[16:31]
	v_max_f32_e32 v129, v129, v129
	v_max_f32_e32 v128, v128, v128
	v_max_f32_e32 v128, v128, v129
	v_sub_f32_e32 v129, v128, v142
	v_cmp_ge_f32_e32 vcc, s20, v129
	s_waitcnt vmcnt(0)
	s_cmp_eq_u64 vcc, exec
	s_cselect_b64 s[42:43], -1, 0
	v_cmp_lt_u32_e32 vcc, s22, v160
	v_cmp_ge_u32_e64 s[40:41], s22, v160
	s_waitcnt vmcnt(0)
	s_barrier
	s_and_saveexec_b64 s[48:49], vcc
	s_cbranch_execz .LBB0_3457
	v_cmp_lt_u32_e32 vcc, s23, v161
	s_add_i32 s14, s6, s25
	s_mov_b32 m0, s14
	v_cndmask_b32_e32 v129, v166, v162, vcc
	v_add_u32_e32 v130, s23, v129
	v_ashrrev_i32_e32 v131, 31, v130
	v_lshlrev_b64 v[130:131], 8, v[130:131]
	v_lshl_add_u64 v[144:145], s[86:87], 0, v[130:131]
	v_lshl_add_u64 v[146:147], v[134:135], 1, v[144:145]
	global_load_lds_dwordx4 v[146:147], off
	v_lshl_add_u64 v[144:145], v[136:137], 1, v[144:145]
	s_add_i32 m0, s14, 0x2000
	v_lshl_add_u64 v[130:131], s[84:85], 0, v[130:131]
	global_load_lds_dwordx4 v[144:145], off
	s_add_i32 m0, s14, 0xc000
	v_lshl_add_u64 v[144:145], v[138:139], 1, v[130:131]
	global_load_lds_dwordx4 v[144:145], off
	v_lshl_add_u64 v[130:131], v[140:141], 1, v[130:131]
	s_add_i32 m0, s14, 0xe000
	s_nop 0
	global_load_lds_dwordx4 v[130:131], off

; #define SBAR() __builtin_amdgcn_sched_barrier(0)
; template <int D0> __device__ __forceinline__ void pv_one(f32x16& od, int vb, bf16x8 pa0, bf16x8 pa1, bf16x8 pa2, bf16x8 pa3) {
;     const s16x4 l0 = tr_read<v_rd_off(D0, 0, 0)>(vb), h0 = tr_read<v_rd_off(D0, 0, 1)>(vb), l1 = tr_read<v_rd_off(D0, 1, 0)>(vb), h1 = tr_read<v_rd_off(D0, 1, 1)>(vb);
;     const s16x4 l2 = tr_read<v_rd_off(D0, 2, 0)>(vb), h2 = tr_read<v_rd_off(D0, 2, 1)>(vb), l3 = tr_read<v_rd_off(D0, 3, 0)>(vb), h3 = tr_read<v_rd_off(D0, 3, 1)>(vb);
;     asm volatile("s_waitcnt lgkmcnt(0)" ::: "memory"); SBAR();
;     ...
;     od = __builtin_amdgcn_mfma_f32_32x32x16_bf16(pa0, PK(l0, h0), od, 0, 0, 0);
;     od = __builtin_amdgcn_mfma_f32_32x32x16_bf16(pa1, PK(l1, h1), od, 0, 0, 0);
;     od = __builtin_amdgcn_mfma_f32_32x32x16_bf16(pa2, PK(l2, h2), od, 0, 0, 0);
;     od = __builtin_amdgcn_mfma_f32_32x32x16_bf16(pa3, PK(l3, h3), od, 0, 0, 0);
;     ...
; }
; __device__ __forceinline__ void pv_d0(f32x16* o, int vb, bf16x8 pa0, bf16x8 pa1, bf16x8 pa2, bf16x8 pa3) {
; __device__ __forceinline__ void finishSM(f32x16& p0, f32x16& p1, float alpha, float& l_reg, bf16x8& pa0, bf16x8& pa1, bf16x8& pa2, bf16x8& pa3) {
; #pragma unroll
;     for (int r = 0; r < 16; ++r) p1[r] = __builtin_amdgcn_exp2f(p1[r]);
;     float ps = 0;
; #pragma unroll
;     for (int r = 0; r < 16; ++r) ps += p0[r];
; #pragma unroll
;     for (int r = 0; r < 16; ++r) ps += p1[r];
;     { auto rr = __builtin_amdgcn_permlane32_swap(__float_as_uint(ps), __float_as_uint(ps), false, false);
;       ps = __uint_as_float(rr[0]) + __uint_as_float(rr[1]); }
;     l_reg = l_reg * alpha + ps;
;     ...
;     PK4(p0, 0, pa0); PK4(p0, 8, pa1); PK4(p1, 0, pa2); PK4(p1, 8, pa3);
;     ...
; }
; template <int DQK> __device__ __forceinline__ void qkt(f32x16& p0, f32x16& p1, const char* Ks, const bf16x8* qr, int r32, int hi) {
;     p0 = f32x16{}; p1 = f32x16{};
; #pragma unroll
;     for (int d0 = 0; d0 < DQK / 16; ++d0) { const int cb = (d0 * 16 + hi * 8) * 2;
;         const bf16x8 b0 = *reinterpret_cast<const bf16x8*>(Ks + kswz<DQK>(r32, cb));
;         const bf16x8 b1 = *reinterpret_cast<const bf16x8*>(Ks + kswz<DQK>(32 + r32, cb));
;         p0 = __builtin_amdgcn_mfma_f32_32x32x16_bf16(b0, qr[d0], p0, 0, 0, 0);
;         p1 = __builtin_amdgcn_mfma_f32_32x32x16_bf16(b1, qr[d0], p1, 0, 0, 0); }
.LBB0_3460:
	s_or_b64 exec, exec, s[46:47]
	v_add_u32_e32 v138, 0, v64
	v_add_u32_e32 v68, v138, v169
	ds_read_b128 v[64:67], v68 offset:49152
	ds_read_b128 v[68:71], v68 offset:57344
	v_add_u32_e32 v134, v138, v171
	s_waitcnt lgkmcnt(0)
	v_mfma_f32_32x32x16_bf16 v[80:95], v[64:67], v[124:127], 0
	v_mfma_f32_32x32x16_bf16 v[64:79], v[68:71], v[124:127], 0
	ds_read_b128 v[124:127], v134 offset:49152
	ds_read_b128 v[134:137], v134 offset:57344
	s_waitcnt lgkmcnt(0)
	v_mfma_f32_32x32x16_bf16 v[80:95], v[124:127], v[120:123], v[80:95]
	v_add_u32_e32 v124, v138, v170
	v_mfma_f32_32x32x16_bf16 v[64:79], v[134:137], v[120:123], v[64:79]
	ds_read_b128 v[120:123], v124 offset:49152
	ds_read_b128 v[124:127], v124 offset:57344
	s_waitcnt lgkmcnt(0)
	v_mfma_f32_32x32x16_bf16 v[80:95], v[120:123], v[116:119], v[80:95]
	v_add_u32_e32 v120, v138, v168
	v_mfma_f32_32x32x16_bf16 v[64:79], v[124:127], v[116:119], v[64:79]
	ds_read_b128 v[116:119], v120 offset:49152
	ds_read_b128 v[120:123], v120 offset:57344
	s_waitcnt lgkmcnt(0)
	v_mfma_f32_32x32x16_bf16 v[80:95], v[116:119], v[112:115], v[80:95]
	v_add_u32_e32 v116, v138, v167
	v_mfma_f32_32x32x16_bf16 v[64:79], v[120:123], v[112:115], v[64:79]
	ds_read_b128 v[112:115], v116 offset:49152
	ds_read_b128 v[116:119], v116 offset:57344
	v_exp_f32_e32 v120, v142
	v_exp_f32_e32 v121, v143
	s_waitcnt lgkmcnt(0)
	v_mfma_f32_32x32x16_bf16 v[80:95], v[112:115], v[108:111], v[80:95]
	v_add_u32_e32 v112, v138, v163
	v_mfma_f32_32x32x16_bf16 v[64:79], v[116:119], v[108:111], v[64:79]
	ds_read_b128 v[108:111], v112 offset:49152
	ds_read_b128 v[112:115], v112 offset:57344
	v_exp_f32_e32 v116, v130
	v_exp_f32_e32 v117, v131
	v_exp_f32_e32 v118, v128
	v_exp_f32_e32 v119, v129
	s_waitcnt lgkmcnt(0)
	v_mfma_f32_32x32x16_bf16 v[80:95], v[108:111], v[104:107], v[80:95]
	v_add_u32_e32 v108, v138, v164
	v_mfma_f32_32x32x16_bf16 v[64:79], v[112:115], v[104:107], v[64:79]
	ds_read_b128 v[104:107], v108 offset:49152
	ds_read_b128 v[108:111], v108 offset:57344
	v_exp_f32_e32 v112, v146
	v_exp_f32_e32 v113, v147
	v_exp_f32_e32 v114, v144
	v_exp_f32_e32 v115, v145
	s_waitcnt lgkmcnt(0)
	v_mfma_f32_32x32x16_bf16 v[80:95], v[104:107], v[100:103], v[80:95]
	v_add_u32_e32 v104, v138, v165
	v_mfma_f32_32x32x16_bf16 v[64:79], v[108:111], v[100:103], v[64:79]
	ds_read_b128 v[100:103], v104 offset:49152
	ds_read_b128 v[104:107], v104 offset:57344
	v_exp_f32_e32 v108, v150
	v_exp_f32_e32 v109, v151
	v_exp_f32_e32 v110, v148
	v_exp_f32_e32 v111, v149
	s_waitcnt lgkmcnt(0)
	v_mfma_f32_32x32x16_bf16 v[80:95], v[100:103], v[96:99], v[80:95]
	v_cvt_pk_bf16_f32 v102, v200, v202
	v_cvt_pk_bf16_f32 v103, v201, v203
	v_mfma_f32_32x32x16_bf16 v[64:79], v[104:107], v[96:99], v[64:79]
	v_add_f32_e32 v96, 0, v206
	v_add_f32_e32 v96, v209, v96
	v_add_f32_e32 v96, v207, v96
	v_add_f32_e32 v96, v210, v96
	v_add_f32_e32 v96, v208, v96
	v_add_f32_e32 v96, v211, v96
	v_add_f32_e32 v96, v204, v96
	v_add_f32_e32 v96, v205, v96
	v_add_f32_e32 v96, v200, v96
	v_add_f32_e32 v96, v202, v96
	v_add_f32_e32 v96, v201, v96
	v_add_f32_e32 v96, v203, v96
	v_exp_f32_e32 v106, v152
	v_add_f32_e32 v96, v196, v96
	v_exp_f32_e32 v107, v153
	v_add_f32_e32 v96, v198, v96
	v_add_f32_e32 v96, v197, v96
	v_add_f32_e32 v96, v199, v96
	v_add_f32_e32 v96, v106, v96
	v_add_f32_e32 v96, v107, v96
	v_add_f32_e32 v96, v108, v96
	v_add_f32_e32 v96, v109, v96
	v_add_f32_e32 v96, v110, v96
	v_add_f32_e32 v96, v111, v96
	v_add_f32_e32 v96, v112, v96
	v_add_f32_e32 v96, v113, v96
	v_add_f32_e32 v96, v114, v96
	v_add_f32_e32 v96, v115, v96
	v_add_f32_e32 v96, v116, v96
	v_add_f32_e32 v96, v117, v96
	v_add_f32_e32 v96, v118, v96
	v_add_f32_e32 v96, v119, v96
	v_add_f32_e32 v96, v120, v96
	v_add_f32_e32 v100, v121, v96
	v_mov_b32_e32 v101, v100
	v_cvt_pk_bf16_f32 v96, v206, v209
	v_cvt_pk_bf16_f32 v97, v207, v210
	v_cvt_pk_bf16_f32 v98, v208, v211
	v_cvt_pk_bf16_f32 v99, v204, v205
	s_nop 1
	v_permlane32_swap_b32_e32 v100, v101
	v_permlane32_swap_b32_e32 v96, v98
	v_permlane32_swap_b32_e32 v97, v99
	v_cvt_pk_bf16_f32 v104, v196, v198
	v_cvt_pk_bf16_f32 v105, v197, v199
	v_cvt_pk_bf16_f32 v106, v106, v107
	v_cvt_pk_bf16_f32 v107, v108, v109
	v_cvt_pk_bf16_f32 v108, v110, v111
	v_cvt_pk_bf16_f32 v109, v112, v113
	v_cvt_pk_bf16_f32 v110, v114, v115
	v_cvt_pk_bf16_f32 v111, v116, v117
	v_cvt_pk_bf16_f32 v112, v118, v119
	v_cvt_pk_bf16_f32 v113, v120, v121
	s_nop 0
	v_permlane32_swap_b32_e32 v102, v104
	v_permlane32_swap_b32_e32 v103, v105
	v_permlane32_swap_b32_e32 v106, v108
	v_permlane32_swap_b32_e32 v107, v109
	v_permlane32_swap_b32_e32 v110, v112
	v_permlane32_swap_b32_e32 v111, v113
	v_add_u32_e32 v130, v174, v159
	ds_read_b64_tr_b16 v[114:115], v130 offset:0
	ds_read_b64_tr_b16 v[116:117], v130 offset:0x800
	ds_read_b64_tr_b16 v[118:119], v130 offset:0x1000
	ds_read_b64_tr_b16 v[120:121], v130 offset:0x1800
	ds_read_b64_tr_b16 v[122:123], v130 offset:0x2000
	ds_read_b64_tr_b16 v[124:125], v130 offset:0x2800
	ds_read_b64_tr_b16 v[126:127], v130 offset:0x3000
	ds_read_b64_tr_b16 v[128:129], v130 offset:0x3800
	s_nop 0
	s_waitcnt lgkmcnt(6)
	v_mfma_f32_32x32x16_bf16 v[0:15], v[96:99], v[114:117], v[0:15]
	ds_read_b64_tr_b16 v[114:115], v130 offset:0x200
	ds_read_b64_tr_b16 v[116:117], v130 offset:0xa00
	s_waitcnt lgkmcnt(6)
	v_mfma_f32_32x32x16_bf16 v[0:15], v[102:105], v[118:121], v[0:15]
	ds_read_b64_tr_b16 v[118:119], v130 offset:0x1200
	ds_read_b64_tr_b16 v[120:121], v130 offset:0x1a00
	s_waitcnt lgkmcnt(6)
	v_mfma_f32_32x32x16_bf16 v[0:15], v[106:109], v[122:125], v[0:15]
	ds_read_b64_tr_b16 v[122:123], v130 offset:0x2200
	ds_read_b64_tr_b16 v[124:125], v130 offset:0x2a00
	s_waitcnt lgkmcnt(6)
; #define SBAR() __builtin_amdgcn_sched_barrier(0)
; template <int D0> __device__ __forceinline__ void pv_one(f32x16& od, int vb, bf16x8 pa0, bf16x8 pa1, bf16x8 pa2, bf16x8 pa3) {
;     const s16x4 l0 = tr_read<v_rd_off(D0, 0, 0)>(vb), h0 = tr_read<v_rd_off(D0, 0, 1)>(vb), l1 = tr_read<v_rd_off(D0, 1, 0)>(vb), h1 = tr_read<v_rd_off(D0, 1, 1)>(vb);
;     const s16x4 l2 = tr_read<v_rd_off(D0, 2, 0)>(vb), h2 = tr_read<v_rd_off(D0, 2, 1)>(vb), l3 = tr_read<v_rd_off(D0, 3, 0)>(vb), h3 = tr_read<v_rd_off(D0, 3, 1)>(vb);
;     asm volatile("s_waitcnt lgkmcnt(0)" ::: "memory"); SBAR();
;     ...
;     od = __builtin_amdgcn_mfma_f32_32x32x16_bf16(pa0, PK(l0, h0), od, 0, 0, 0);
;     od = __builtin_amdgcn_mfma_f32_32x32x16_bf16(pa1, PK(l1, h1), od, 0, 0, 0);
;     od = __builtin_amdgcn_mfma_f32_32x32x16_bf16(pa2, PK(l2, h2), od, 0, 0, 0);
;     od = __builtin_amdgcn_mfma_f32_32x32x16_bf16(pa3, PK(l3, h3), od, 0, 0, 0);
;     ...
; }
; __device__ __forceinline__ void pv_d0(f32x16* o, int vb, bf16x8 pa0, bf16x8 pa1, bf16x8 pa2, bf16x8 pa3) {
;     pv_one<0>(o[0], vb, pa0, pa1, pa2, pa3); pv_one<1>(o[1], vb, pa0, pa1, pa2, pa3); pv_one<2>(o[2], vb, pa0, pa1, pa2, pa3); pv_one<3>(o[3], vb, pa0, pa1, pa2, pa3);
; }
; __device__ __forceinline__ void partialSM(f32x16& p0, f32x16& p1, float& m_reg, float& mn, float& alpha, const float C, const float thr_raw) {
;     float pmax = p0[0];
; #pragma unroll
;     for (int r = 1; r < 16; ++r) pmax = fmaxf(pmax, p0[r]);
; #pragma unroll
;     for (int r = 0; r < 16; ++r) pmax = fmaxf(pmax, p1[r]);
;     { auto rr = __builtin_amdgcn_permlane32_swap(__float_as_uint(pmax), __float_as_uint(pmax), false, false);
;       pmax = fmaxf(__uint_as_float(rr[0]), __uint_as_float(rr[1])); }
;     if (__builtin_expect(__all(pmax - m_reg <= thr_raw), 1)) { mn = m_reg; alpha = 1.f; }
;     else { mn = fmaxf(m_reg, pmax); alpha = __builtin_amdgcn_exp2f((m_reg - mn) * C); m_reg = mn; }
	v_mfma_f32_32x32x16_bf16 v[0:15], v[110:113], v[126:129], v[0:15]
	ds_read_b64_tr_b16 v[126:127], v130 offset:0x3200
	ds_read_b64_tr_b16 v[128:129], v130 offset:0x3a00
	s_waitcnt lgkmcnt(6)
	v_mfma_f32_32x32x16_bf16 v[48:63], v[96:99], v[114:117], v[48:63]
	ds_read_b64_tr_b16 v[114:115], v130 offset:0x400
	ds_read_b64_tr_b16 v[116:117], v130 offset:0xc00
	s_waitcnt lgkmcnt(6)
	v_mfma_f32_32x32x16_bf16 v[48:63], v[102:105], v[118:121], v[48:63]
	ds_read_b64_tr_b16 v[118:119], v130 offset:0x1400
	ds_read_b64_tr_b16 v[120:121], v130 offset:0x1c00
	s_waitcnt lgkmcnt(6)
	v_mfma_f32_32x32x16_bf16 v[48:63], v[106:109], v[122:125], v[48:63]
	ds_read_b64_tr_b16 v[122:123], v130 offset:0x2400
	ds_read_b64_tr_b16 v[124:125], v130 offset:0x2c00
	s_waitcnt lgkmcnt(6)
	v_mfma_f32_32x32x16_bf16 v[48:63], v[110:113], v[126:129], v[48:63]
	ds_read_b64_tr_b16 v[126:127], v130 offset:0x3400
	ds_read_b64_tr_b16 v[128:129], v130 offset:0x3c00
	s_waitcnt lgkmcnt(6)
	v_mfma_f32_32x32x16_bf16 v[32:47], v[96:99], v[114:117], v[32:47]
	ds_read_b64_tr_b16 v[114:115], v130 offset:0x600
	ds_read_b64_tr_b16 v[116:117], v130 offset:0xe00
	s_waitcnt lgkmcnt(6)
	v_mfma_f32_32x32x16_bf16 v[32:47], v[102:105], v[118:121], v[32:47]
	ds_read_b64_tr_b16 v[118:119], v130 offset:0x1600
	ds_read_b64_tr_b16 v[120:121], v130 offset:0x1e00
	s_waitcnt lgkmcnt(6)
	v_mfma_f32_32x32x16_bf16 v[32:47], v[106:109], v[122:125], v[32:47]
	ds_read_b64_tr_b16 v[122:123], v130 offset:0x2600
	ds_read_b64_tr_b16 v[124:125], v130 offset:0x2e00
	s_waitcnt lgkmcnt(6)
	v_mfma_f32_32x32x16_bf16 v[32:47], v[110:113], v[126:129], v[32:47]
	ds_read_b64_tr_b16 v[126:127], v130 offset:0x3600
	ds_read_b64_tr_b16 v[128:129], v130 offset:0x3e00
	s_waitcnt lgkmcnt(6)
	v_mfma_f32_32x32x16_bf16 v[16:31], v[96:99], v[114:117], v[16:31]
	v_max_f32_e32 v96, v81, v81
	v_max_f32_e32 v97, v80, v80
	v_max_f32_e32 v96, v97, v96
	v_max3_f32 v96, v96, v82, v83
	v_max3_f32 v96, v96, v84, v85
	v_max3_f32 v96, v96, v86, v87
	v_max3_f32 v96, v96, v88, v89
	v_max3_f32 v96, v96, v90, v91
	v_max3_f32 v96, v96, v92, v93
	s_waitcnt lgkmcnt(4)
	v_mfma_f32_32x32x16_bf16 v[16:31], v[102:105], v[118:121], v[16:31]
	v_max3_f32 v96, v96, v94, v95
	v_max3_f32 v96, v96, v64, v65
	v_max3_f32 v96, v96, v66, v67
	v_max3_f32 v96, v96, v68, v69
	v_max3_f32 v96, v96, v70, v71
	v_max3_f32 v96, v96, v72, v73
	v_max3_f32 v96, v96, v74, v75
	v_max3_f32 v96, v96, v76, v77
	s_waitcnt lgkmcnt(2)
	v_mfma_f32_32x32x16_bf16 v[16:31], v[106:109], v[122:125], v[16:31]
	v_max3_f32 v96, v96, v78, v79
	v_mov_b32_e32 v97, v96
	s_nop 1
	v_permlane32_swap_b32_e32 v96, v97
	v_max_f32_e32 v97, v97, v97
	v_max_f32_e32 v96, v96, v96
	v_max_f32_e32 v96, v96, v97
	v_sub_f32_e32 v97, v96, v172
	v_cmp_ge_f32_e32 vcc, s20, v97
	v_max_f32_e32 v97, v172, v172
	v_max_f32_e32 v97, v97, v96
	s_waitcnt lgkmcnt(0)
	v_mfma_f32_32x32x16_bf16 v[16:31], v[110:113], v[126:129], v[16:31]
	v_sub_f32_e32 v96, v172, v97
	v_mul_f32_e32 v96, 0x3e0293ee, v96
	v_exp_f32_e32 v96, v96
	s_cmp_eq_u64 vcc, exec
	s_cselect_b64 s[40:41], -1, 0
	v_cndmask_b32_e64 v96, v96, 1.0, s[40:41]
	v_cmp_gt_f32_e32 vcc, 1.0, v96
	s_cbranch_vccz .LBB0_3464
	s_and_saveexec_b64 s[42:43], s[38:39]
	ds_write_b32 v157, v96 offset:128
	s_or_b64 exec, exec, s[42:43]
	s_waitcnt lgkmcnt(0)
	v_add_u32_e32 v98, s1, v178
	ds_read_b128 v[102:105], v98 offset:224
	ds_read_b128 v[106:109], v98 offset:192
	ds_read_b128 v[110:113], v98 offset:160
	ds_read_b128 v[114:117], v98 offset:128
	s_waitcnt lgkmcnt(0)
	v_pk_mul_f32 v[12:13], v[12:13], v[102:103]
	v_pk_mul_f32 v[8:9], v[8:9], v[106:107]
	v_pk_mul_f32 v[4:5], v[4:5], v[110:111]
	v_pk_mul_f32 v[14:15], v[14:15], v[104:105]
	v_pk_mul_f32 v[10:11], v[10:11], v[108:109]
	v_pk_mul_f32 v[6:7], v[6:7], v[112:113]
	v_pk_mul_f32 v[2:3], v[2:3], v[116:117]
	v_pk_mul_f32 v[0:1], v[0:1], v[114:115]
	v_pk_mul_f32 v[60:61], v[60:61], v[102:103]
	v_pk_mul_f32 v[56:57], v[56:57], v[106:107]
	v_pk_mul_f32 v[52:53], v[52:53], v[110:111]
	v_pk_mul_f32 v[62:63], v[62:63], v[104:105]
	v_pk_mul_f32 v[58:59], v[58:59], v[108:109]
	v_pk_mul_f32 v[54:55], v[54:55], v[112:113]
	v_pk_mul_f32 v[50:51], v[50:51], v[116:117]
	v_pk_mul_f32 v[48:49], v[48:49], v[114:115]
	v_pk_mul_f32 v[44:45], v[44:45], v[102:103]
	v_pk_mul_f32 v[40:41], v[40:41], v[106:107]
	v_pk_mul_f32 v[36:37], v[36:37], v[110:111]
	v_pk_mul_f32 v[46:47], v[46:47], v[104:105]
	v_pk_mul_f32 v[42:43], v[42:43], v[108:109]
	v_pk_mul_f32 v[38:39], v[38:39], v[112:113]
	v_pk_mul_f32 v[34:35], v[34:35], v[116:117]
	v_pk_mul_f32 v[32:33], v[32:33], v[114:115]
	v_pk_mul_f32 v[28:29], v[28:29], v[102:103]
	v_pk_mul_f32 v[24:25], v[24:25], v[106:107]
	v_pk_mul_f32 v[20:21], v[20:21], v[110:111]
	v_pk_mul_f32 v[30:31], v[30:31], v[104:105]
	v_pk_mul_f32 v[26:27], v[26:27], v[108:109]
	v_pk_mul_f32 v[22:23], v[22:23], v[112:113]
	v_pk_mul_f32 v[18:19], v[18:19], v[116:117]
	v_pk_mul_f32 v[16:17], v[16:17], v[114:115]
; #define SBAR() __builtin_amdgcn_sched_barrier(0)
; template <int D0> __device__ __forceinline__ void pv_one(f32x16& od, int vb, bf16x8 pa0, bf16x8 pa1, bf16x8 pa2, bf16x8 pa3) {
;     const s16x4 l0 = tr_read<v_rd_off(D0, 0, 0)>(vb), h0 = tr_read<v_rd_off(D0, 0, 1)>(vb), l1 = tr_read<v_rd_off(D0, 1, 0)>(vb), h1 = tr_read<v_rd_off(D0, 1, 1)>(vb);
;     const s16x4 l2 = tr_read<v_rd_off(D0, 2, 0)>(vb), h2 = tr_read<v_rd_off(D0, 2, 1)>(vb), l3 = tr_read<v_rd_off(D0, 3, 0)>(vb), h3 = tr_read<v_rd_off(D0, 3, 1)>(vb);
;     asm volatile("s_waitcnt lgkmcnt(0)" ::: "memory"); SBAR();
;     ...
;     od = __builtin_amdgcn_mfma_f32_32x32x16_bf16(pa0, PK(l0, h0), od, 0, 0, 0);
;     od = __builtin_amdgcn_mfma_f32_32x32x16_bf16(pa1, PK(l1, h1), od, 0, 0, 0);
;     od = __builtin_amdgcn_mfma_f32_32x32x16_bf16(pa2, PK(l2, h2), od, 0, 0, 0);
;     od = __builtin_amdgcn_mfma_f32_32x32x16_bf16(pa3, PK(l3, h3), od, 0, 0, 0);
;     ...
; }
; __device__ __forceinline__ void pv_d0(f32x16* o, int vb, bf16x8 pa0, bf16x8 pa1, bf16x8 pa2, bf16x8 pa3) {
;     pv_one<0>(o[0], vb, pa0, pa1, pa2, pa3); pv_one<1>(o[1], vb, pa0, pa1, pa2, pa3); pv_one<2>(o[2], vb, pa0, pa1, pa2, pa3); pv_one<3>(o[3], vb, pa0, pa1, pa2, pa3);
; __device__ __forceinline__ void partialSM(f32x16& p0, f32x16& p1, float& m_reg, float& mn, float& alpha, const float C, const float thr_raw) {
;     ...
;     const float mnC = -mn * C;
; #pragma unroll
;     for (int r = 0; r < 16; ++r) p0[r] = fmaf(p0[r], C, mnC);
; #pragma unroll
;     for (int r = 0; r < 16; ++r) p1[r] = fmaf(p1[r], C, mnC);
; #pragma unroll
;     for (int r = 0; r < 16; ++r) p0[r] = __builtin_amdgcn_exp2f(p0[r]);
; }
; __device__ __forceinline__ void finishSM(f32x16& p0, f32x16& p1, float alpha, float& l_reg, bf16x8& pa0, bf16x8& pa1, bf16x8& pa2, bf16x8& pa3) {
; #pragma unroll
;     for (int r = 0; r < 16; ++r) p1[r] = __builtin_amdgcn_exp2f(p1[r]);
;     float ps = 0;
; #pragma unroll
;     for (int r = 0; r < 16; ++r) ps += p0[r];
; #pragma unroll
;     for (int r = 0; r < 16; ++r) ps += p1[r];
;     { auto rr = __builtin_amdgcn_permlane32_swap(__float_as_uint(ps), __float_as_uint(ps), false, false);
;       ps = __uint_as_float(rr[0]) + __uint_as_float(rr[1]); }
;     l_reg = l_reg * alpha + ps;
;     ...
;     PK4(p0, 0, pa0); PK4(p0, 8, pa1); PK4(p1, 0, pa2); PK4(p1, 8, pa3);
;     ...
; }
.LBB0_3464:
	v_cndmask_b32_e64 v97, v97, v172, s[40:41]
	v_mul_f32_e32 v97, 0xbe0293ee, v97
	v_fmamk_f32 v80, v80, 0x3e0293ee, v97
	v_fmamk_f32 v81, v81, 0x3e0293ee, v97
	v_fmamk_f32 v82, v82, 0x3e0293ee, v97
	v_fmamk_f32 v83, v83, 0x3e0293ee, v97
	v_fmamk_f32 v84, v84, 0x3e0293ee, v97
	v_fmamk_f32 v85, v85, 0x3e0293ee, v97
	v_fmamk_f32 v86, v86, 0x3e0293ee, v97
	v_fmamk_f32 v87, v87, 0x3e0293ee, v97
	v_fmamk_f32 v88, v88, 0x3e0293ee, v97
	v_fmamk_f32 v89, v89, 0x3e0293ee, v97
	v_fmamk_f32 v90, v90, 0x3e0293ee, v97
	v_fmamk_f32 v91, v91, 0x3e0293ee, v97
	v_fmamk_f32 v92, v92, 0x3e0293ee, v97
	v_fmamk_f32 v93, v93, 0x3e0293ee, v97
	v_fmamk_f32 v94, v94, 0x3e0293ee, v97
	v_fmamk_f32 v95, v95, 0x3e0293ee, v97
	v_fmamk_f32 v64, v64, 0x3e0293ee, v97
	v_fmamk_f32 v65, v65, 0x3e0293ee, v97
	v_fmamk_f32 v66, v66, 0x3e0293ee, v97
	v_fmamk_f32 v67, v67, 0x3e0293ee, v97
	v_fmamk_f32 v68, v68, 0x3e0293ee, v97
	v_fmamk_f32 v69, v69, 0x3e0293ee, v97
	v_fmamk_f32 v70, v70, 0x3e0293ee, v97
	v_fmamk_f32 v71, v71, 0x3e0293ee, v97
	v_fmamk_f32 v72, v72, 0x3e0293ee, v97
	v_fmamk_f32 v73, v73, 0x3e0293ee, v97
	v_fmamk_f32 v74, v74, 0x3e0293ee, v97
	v_fmamk_f32 v75, v75, 0x3e0293ee, v97
	v_fmamk_f32 v76, v76, 0x3e0293ee, v97
	v_fmamk_f32 v77, v77, 0x3e0293ee, v97
	v_fmamk_f32 v78, v78, 0x3e0293ee, v97
	v_fmac_f32_e32 v97, 0x3e0293ee, v79
	v_exp_f32_e32 v79, v80
	v_exp_f32_e32 v80, v81
	v_exp_f32_e32 v81, v82
	v_exp_f32_e32 v82, v83
	v_exp_f32_e32 v83, v84
	v_exp_f32_e32 v84, v85
	v_exp_f32_e32 v85, v86
	v_exp_f32_e32 v86, v87
	v_exp_f32_e32 v87, v88
	v_exp_f32_e32 v88, v89
	v_exp_f32_e32 v89, v90
	v_exp_f32_e32 v90, v91
	v_exp_f32_e32 v91, v92
	v_exp_f32_e32 v92, v93
	v_exp_f32_e32 v93, v94
	v_exp_f32_e32 v94, v95
	v_exp_f32_e32 v95, v64
	v_add_f32_e32 v64, 0, v79
	v_add_f32_e32 v64, v80, v64
	v_add_f32_e32 v64, v81, v64
	v_add_f32_e32 v64, v82, v64
	v_add_f32_e32 v64, v83, v64
	v_add_f32_e32 v64, v84, v64
	v_add_f32_e32 v64, v85, v64
	v_add_f32_e32 v64, v86, v64
	v_add_f32_e32 v64, v87, v64
	v_add_f32_e32 v64, v88, v64
	v_add_f32_e32 v64, v89, v64
	v_add_f32_e32 v64, v90, v64
	v_add_f32_e32 v64, v91, v64
	v_exp_f32_e32 v98, v65
	v_add_f32_e32 v64, v92, v64
	v_exp_f32_e32 v99, v66
	v_add_f32_e32 v64, v93, v64
	v_exp_f32_e32 v102, v67
	v_add_f32_e32 v64, v94, v64
	v_exp_f32_e32 v103, v68
	v_add_f32_e32 v64, v95, v64
	v_exp_f32_e32 v104, v69
	v_add_f32_e32 v64, v98, v64
	v_exp_f32_e32 v105, v70
	v_add_f32_e32 v64, v99, v64
	v_exp_f32_e32 v106, v71
	v_add_f32_e32 v64, v102, v64
	v_exp_f32_e32 v107, v72
	v_add_f32_e32 v64, v103, v64
	v_exp_f32_e32 v108, v73
	v_add_f32_e32 v64, v104, v64
	v_exp_f32_e32 v109, v74
	v_add_f32_e32 v64, v105, v64
	v_exp_f32_e32 v110, v75
	v_add_f32_e32 v64, v106, v64
	v_exp_f32_e32 v111, v76
	v_add_f32_e32 v64, v107, v64
	v_exp_f32_e32 v112, v77
	v_add_f32_e32 v64, v108, v64
	v_exp_f32_e32 v113, v78
	v_add_f32_e32 v64, v109, v64
	v_exp_f32_e32 v97, v97
	v_add_f32_e32 v64, v110, v64
	v_add_f32_e32 v64, v111, v64
	v_add_f32_e32 v64, v112, v64
	v_add_f32_e32 v64, v113, v64
	v_add_f32_e32 v64, v97, v64
	v_mov_b32_e32 v65, v64
	s_nop 1
	v_permlane32_swap_b32_e32 v64, v65
	v_cvt_pk_bf16_f32 v66, v79, v80
	v_cvt_pk_bf16_f32 v67, v81, v82
	v_cvt_pk_bf16_f32 v68, v83, v84
	v_cvt_pk_bf16_f32 v69, v85, v86
	v_cvt_pk_bf16_f32 v70, v87, v88
	v_cvt_pk_bf16_f32 v71, v89, v90
	v_cvt_pk_bf16_f32 v72, v91, v92
	v_cvt_pk_bf16_f32 v73, v93, v94
	v_cvt_pk_bf16_f32 v74, v95, v98
	v_cvt_pk_bf16_f32 v75, v99, v102
	v_cvt_pk_bf16_f32 v76, v103, v104
	v_cvt_pk_bf16_f32 v77, v105, v106
	v_cvt_pk_bf16_f32 v78, v107, v108
	v_cvt_pk_bf16_f32 v79, v109, v110
	v_cvt_pk_bf16_f32 v80, v111, v112
	v_cvt_pk_bf16_f32 v81, v113, v97
	s_nop 0
	v_permlane32_swap_b32_e32 v66, v68
	v_permlane32_swap_b32_e32 v67, v69
	v_permlane32_swap_b32_e32 v70, v72
	v_permlane32_swap_b32_e32 v71, v73
	v_permlane32_swap_b32_e32 v74, v76
	v_permlane32_swap_b32_e32 v75, v77
	v_permlane32_swap_b32_e32 v78, v80
	v_permlane32_swap_b32_e32 v79, v81
	ds_read_b64_tr_b16 v[82:83], v158 offset:0
	ds_read_b64_tr_b16 v[84:85], v158 offset:0x800
	ds_read_b64_tr_b16 v[86:87], v158 offset:0x1000
	ds_read_b64_tr_b16 v[88:89], v158 offset:0x1800
	ds_read_b64_tr_b16 v[90:91], v158 offset:0x2000
	ds_read_b64_tr_b16 v[92:93], v158 offset:0x2800
	ds_read_b64_tr_b16 v[102:103], v158 offset:0x3000
	ds_read_b64_tr_b16 v[104:105], v158 offset:0x3800
	s_nop 0
	s_waitcnt lgkmcnt(6)
	v_mfma_f32_32x32x16_bf16 v[0:15], v[66:69], v[82:85], v[0:15]
	ds_read_b64_tr_b16 v[82:83], v158 offset:0x200
	ds_read_b64_tr_b16 v[84:85], v158 offset:0xa00
	s_waitcnt lgkmcnt(6)
	v_mfma_f32_32x32x16_bf16 v[0:15], v[70:73], v[86:89], v[0:15]
	ds_read_b64_tr_b16 v[86:87], v158 offset:0x1200
	ds_read_b64_tr_b16 v[88:89], v158 offset:0x1a00
	s_waitcnt lgkmcnt(6)
	v_mfma_f32_32x32x16_bf16 v[0:15], v[74:77], v[90:93], v[0:15]
	ds_read_b64_tr_b16 v[90:91], v158 offset:0x2200
	ds_read_b64_tr_b16 v[92:93], v158 offset:0x2a00
	s_waitcnt lgkmcnt(6)
	v_mfma_f32_32x32x16_bf16 v[0:15], v[78:81], v[102:105], v[0:15]
	ds_read_b64_tr_b16 v[102:103], v158 offset:0x3200
	ds_read_b64_tr_b16 v[104:105], v158 offset:0x3a00
	s_waitcnt lgkmcnt(6)
	v_mfma_f32_32x32x16_bf16 v[48:63], v[66:69], v[82:85], v[48:63]
	ds_read_b64_tr_b16 v[82:83], v158 offset:0x400
	ds_read_b64_tr_b16 v[84:85], v158 offset:0xc00
	s_waitcnt lgkmcnt(6)
	v_mfma_f32_32x32x16_bf16 v[48:63], v[70:73], v[86:89], v[48:63]
	ds_read_b64_tr_b16 v[86:87], v158 offset:0x1400
	ds_read_b64_tr_b16 v[88:89], v158 offset:0x1c00
	s_waitcnt lgkmcnt(6)
	v_mfma_f32_32x32x16_bf16 v[48:63], v[74:77], v[90:93], v[48:63]
	ds_read_b64_tr_b16 v[90:91], v158 offset:0x2400
	ds_read_b64_tr_b16 v[92:93], v158 offset:0x2c00
	s_waitcnt lgkmcnt(6)
; __device__ __forceinline__ bf16_t f2bf(float x) { return (bf16_t)(cvt_pk_bf16(x, 0.f) & 0xffffu); }
; __device__ __forceinline__ int crow(int r, int hi) { return (r & 3) + 8 * (r >> 2) + 4 * hi; }
; template <int D0> __device__ __forceinline__ void pv_one(f32x16& od, int vb, bf16x8 pa0, bf16x8 pa1, bf16x8 pa2, bf16x8 pa3) {
;     ...
;     od = __builtin_amdgcn_mfma_f32_32x32x16_bf16(pa0, PK(l0, h0), od, 0, 0, 0);
;     od = __builtin_amdgcn_mfma_f32_32x32x16_bf16(pa1, PK(l1, h1), od, 0, 0, 0);
;     od = __builtin_amdgcn_mfma_f32_32x32x16_bf16(pa2, PK(l2, h2), od, 0, 0, 0);
;     od = __builtin_amdgcn_mfma_f32_32x32x16_bf16(pa3, PK(l3, h3), od, 0, 0, 0);
; template <int LDQ, int LDK, int LDV> ...
;     ...
;     if (hi == 0) li_l[r32] = l_reg; asm volatile("s_waitcnt lgkmcnt(0)" ::: "memory");
;     float rli[16];
; #pragma unroll
;     for (int r = 0; r < 16; ++r) rli[r] = __builtin_amdgcn_rcpf(li_l[crow(r, hi)]);
;     bf16_t* Ow = Ob + (size_t)(wid * 32) * DM;
; #pragma unroll
;     for (int r = 0; r < 16; ++r) { const int orow = crow(r, hi);
; #pragma unroll
;         for (int d0 = 0; d0 < 4; ++d0) Ow[(size_t)orow * DM + d0 * 32 + r32] = f2bf(o[d0][r] * rli[r]); }
	v_mfma_f32_32x32x16_bf16 v[48:63], v[78:81], v[102:105], v[48:63]
	ds_read_b64_tr_b16 v[102:103], v158 offset:0x3400
	ds_read_b64_tr_b16 v[104:105], v158 offset:0x3c00
	s_waitcnt lgkmcnt(6)
	v_mfma_f32_32x32x16_bf16 v[32:47], v[66:69], v[82:85], v[32:47]
	ds_read_b64_tr_b16 v[82:83], v158 offset:0x600
	ds_read_b64_tr_b16 v[84:85], v158 offset:0xe00
	s_waitcnt lgkmcnt(6)
	v_mfma_f32_32x32x16_bf16 v[32:47], v[70:73], v[86:89], v[32:47]
	ds_read_b64_tr_b16 v[86:87], v158 offset:0x1600
	ds_read_b64_tr_b16 v[88:89], v158 offset:0x1e00
	s_waitcnt lgkmcnt(6)
	v_mfma_f32_32x32x16_bf16 v[32:47], v[74:77], v[90:93], v[32:47]
	ds_read_b64_tr_b16 v[90:91], v158 offset:0x2600
	ds_read_b64_tr_b16 v[92:93], v158 offset:0x2e00
	s_waitcnt lgkmcnt(6)
	v_mfma_f32_32x32x16_bf16 v[32:47], v[78:81], v[102:105], v[32:47]
	ds_read_b64_tr_b16 v[102:103], v158 offset:0x3600
	ds_read_b64_tr_b16 v[104:105], v158 offset:0x3e00
	s_waitcnt lgkmcnt(6)
	v_mfma_f32_32x32x16_bf16 v[16:31], v[66:69], v[82:85], v[16:31]
	s_waitcnt lgkmcnt(4)
	v_mfma_f32_32x32x16_bf16 v[16:31], v[70:73], v[86:89], v[16:31]
	s_waitcnt lgkmcnt(2)
	v_mfma_f32_32x32x16_bf16 v[16:31], v[74:77], v[90:93], v[16:31]
	s_waitcnt lgkmcnt(0)
	v_mfma_f32_32x32x16_bf16 v[16:31], v[78:81], v[102:105], v[16:31]
	s_and_saveexec_b64 s[40:41], s[38:39]
	v_add_f32_e32 v66, v100, v101
	v_fmac_f32_e32 v66, v133, v194
	v_add_f32_e32 v64, v64, v65
	v_fmac_f32_e32 v64, v66, v96
	ds_write_b32 v157, v64
	s_or_b64 exec, exec, s[40:41]
	v_ashrrev_i32_e32 v133, 31, v132
	v_readlane_b32 s6, v251, 44
	v_lshlrev_b64 v[64:65], 12, v[132:133]
	v_readlane_b32 s7, v251, 45
	s_waitcnt lgkmcnt(0)
	v_add_u32_e32 v74, s1, v178
	v_lshlrev_b32_e32 v70, 8, v154
	v_lshl_add_u64 v[68:69], s[6:7], 0, v[64:65]
	ds_read_b128 v[64:67], v74
	v_mov_b32_e32 v71, v179
	v_lshl_add_u64 v[72:73], v[68:69], 0, v[70:71]
	ds_read_b128 v[68:71], v74 offset:32
	s_ashr_i32 s1, s0, 31
	s_waitcnt lgkmcnt(0)
	v_rcp_f32_e32 v75, v64
	v_rcp_f32_e32 v76, v65
	v_rcp_f32_e32 v77, v66
	v_rcp_f32_e32 v78, v67
	ds_read_b128 v[64:67], v74 offset:64
	s_lshl_b64 s[0:1], s[0:1], 12
	v_rcp_f32_e32 v79, v68
	v_rcp_f32_e32 v80, v69
	v_rcp_f32_e32 v81, v70
	v_rcp_f32_e32 v82, v71
	ds_read_b128 v[68:71], v74 offset:96
	s_waitcnt lgkmcnt(0)
	v_rcp_f32_e32 v74, v64
	v_rcp_f32_e32 v83, v65
	v_lshl_add_u64 v[64:65], v[72:73], 0, s[0:1]
	v_lshlrev_b32_e32 v178, 1, v155
	v_rcp_f32_e32 v84, v66
	v_rcp_f32_e32 v85, v67
	v_lshlrev_b32_e32 v66, 14, v156
	v_lshl_add_u64 v[64:65], v[64:65], 0, v[178:179]
	v_mov_b32_e32 v67, v179
	v_mul_f32_e32 v0, v0, v75
	v_lshl_add_u64 v[64:65], v[64:65], 0, v[66:67]
	v_cvt_pk_bf16_f32 v0, v0, v179
	global_store_short v[64:65], v0, off
	v_mul_f32_e32 v0, v48, v75
	v_cvt_pk_bf16_f32 v0, v0, v179
	global_store_short v[64:65], v0, off offset:64
	v_mul_f32_e32 v0, v32, v75
	v_cvt_pk_bf16_f32 v0, v0, v179
	global_store_short v[64:65], v0, off offset:128
	v_mul_f32_e32 v0, v16, v75
	v_cvt_pk_bf16_f32 v0, v0, v179
	global_store_short v[64:65], v0, off offset:192
	v_mul_f32_e32 v0, v1, v76
	v_cvt_pk_bf16_f32 v16, v0, v179
	v_add_co_u32_e32 v0, vcc, s17, v64
	s_movk_i32 s0, 0x2000
	s_nop 0
	v_addc_co_u32_e32 v1, vcc, 0, v65, vcc
	v_add_co_u32_e32 v66, vcc, s0, v64
	s_movk_i32 s0, 0x3000
	s_nop 0
	v_addc_co_u32_e32 v67, vcc, 0, v65, vcc
	global_store_short v[66:67], v16, off offset:-4096
	v_mul_f32_e32 v16, v49, v76
	v_cvt_pk_bf16_f32 v16, v16, v179
	global_store_short v[0:1], v16, off offset:64
	v_mul_f32_e32 v16, v33, v76
	v_cvt_pk_bf16_f32 v16, v16, v179
	global_store_short v[0:1], v16, off offset:128
	v_mul_f32_e32 v16, v17, v76
	v_cvt_pk_bf16_f32 v16, v16, v179
	global_store_short v[0:1], v16, off offset:192
	v_mul_f32_e32 v0, v2, v77
	v_cvt_pk_bf16_f32 v0, v0, v179
	global_store_short v[66:67], v0, off
	v_mul_f32_e32 v0, v50, v77
	v_cvt_pk_bf16_f32 v0, v0, v179
	global_store_short v[66:67], v0, off offset:64
	v_mul_f32_e32 v0, v34, v77
	v_cvt_pk_bf16_f32 v0, v0, v179
	global_store_short v[66:67], v0, off offset:128
	v_mul_f32_e32 v0, v18, v77
	v_cvt_pk_bf16_f32 v0, v0, v179
	global_store_short v[66:67], v0, off offset:192
	v_mul_f32_e32 v0, v3, v78
	v_cvt_pk_bf16_f32 v2, v0, v179
	v_add_co_u32_e32 v0, vcc, s0, v64
	s_mov_b32 s0, 0x8000
	s_nop 0
	v_addc_co_u32_e32 v1, vcc, 0, v65, vcc
	global_store_short v[0:1], v2, off
	v_mul_f32_e32 v2, v51, v78
	v_cvt_pk_bf16_f32 v2, v2, v179
	global_store_short v[0:1], v2, off offset:64
	v_mul_f32_e32 v2, v35, v78
	v_cvt_pk_bf16_f32 v2, v2, v179
	global_store_short v[0:1], v2, off offset:128
	v_mul_f32_e32 v2, v19, v78
	v_cvt_pk_bf16_f32 v2, v2, v179
	global_store_short v[0:1], v2, off offset:192
	v_mul_f32_e32 v0, v4, v79
	v_cvt_pk_bf16_f32 v4, v0, v179
	v_add_co_u32_e32 v0, vcc, s0, v64
	s_mov_b32 s0, 0x9000
	s_nop 0
	v_addc_co_u32_e32 v1, vcc, 0, v65, vcc
	v_add_co_u32_e32 v2, vcc, s0, v64
	s_mov_b32 s0, 0xa000
	s_nop 0
	v_addc_co_u32_e32 v3, vcc, 0, v65, vcc
	global_store_short v[2:3], v4, off offset:-4096
	v_mul_f32_e32 v4, v52, v79
	v_cvt_pk_bf16_f32 v4, v4, v179
	global_store_short v[0:1], v4, off offset:64
	v_mul_f32_e32 v4, v36, v79
	v_cvt_pk_bf16_f32 v4, v4, v179
	global_store_short v[0:1], v4, off offset:128
	v_mul_f32_e32 v4, v20, v79
	v_cvt_pk_bf16_f32 v4, v4, v179
	global_store_short v[0:1], v4, off offset:192
	v_mul_f32_e32 v0, v5, v80
	v_cvt_pk_bf16_f32 v0, v0, v179
	global_store_short v[2:3], v0, off
	v_mul_f32_e32 v0, v53, v80
	v_cvt_pk_bf16_f32 v0, v0, v179
	global_store_short v[2:3], v0, off offset:64
	v_mul_f32_e32 v0, v37, v80
	v_cvt_pk_bf16_f32 v0, v0, v179
; __device__ __forceinline__ bf16_t f2bf(float x) { return (bf16_t)(cvt_pk_bf16(x, 0.f) & 0xffffu); }
; __device__ __forceinline__ int crow(int r, int hi) { return (r & 3) + 8 * (r >> 2) + 4 * hi; }
; template <int LDQ, int LDK, int LDV> ...
;     ...
;     bf16_t* Ow = Ob + (size_t)(wid * 32) * DM;
; #pragma unroll
;     for (int r = 0; r < 16; ++r) { const int orow = crow(r, hi);
; #pragma unroll
;         for (int d0 = 0; d0 < 4; ++d0) Ow[(size_t)orow * DM + d0 * 32 + r32] = f2bf(o[d0][r] * rli[r]); }
	global_store_short v[2:3], v0, off offset:128
	v_mul_f32_e32 v0, v21, v80
	v_cvt_pk_bf16_f32 v0, v0, v179
	global_store_short v[2:3], v0, off offset:192
	v_mul_f32_e32 v0, v6, v81
	v_cvt_pk_bf16_f32 v4, v0, v179
	v_add_co_u32_e32 v0, vcc, s0, v64
	s_mov_b32 s0, 0xb000
	s_nop 0
	v_addc_co_u32_e32 v1, vcc, 0, v65, vcc
	v_add_co_u32_e32 v2, vcc, s0, v64
	s_mov_b32 s0, 0x10000
	s_nop 0
	v_addc_co_u32_e32 v3, vcc, 0, v65, vcc
	global_store_short v[2:3], v4, off offset:-4096
	v_mul_f32_e32 v4, v54, v81
	v_cvt_pk_bf16_f32 v4, v4, v179
	global_store_short v[0:1], v4, off offset:64
	v_mul_f32_e32 v4, v38, v81
	v_cvt_pk_bf16_f32 v4, v4, v179
	global_store_short v[0:1], v4, off offset:128
	v_mul_f32_e32 v4, v22, v81
	v_cvt_pk_bf16_f32 v4, v4, v179
	global_store_short v[0:1], v4, off offset:192
	v_mul_f32_e32 v0, v7, v82
	v_cvt_pk_bf16_f32 v0, v0, v179
	global_store_short v[2:3], v0, off
	v_mul_f32_e32 v0, v55, v82
	v_cvt_pk_bf16_f32 v0, v0, v179
	global_store_short v[2:3], v0, off offset:64
	v_mul_f32_e32 v0, v39, v82
	v_cvt_pk_bf16_f32 v0, v0, v179
	global_store_short v[2:3], v0, off offset:128
	v_mul_f32_e32 v0, v23, v82
	v_cvt_pk_bf16_f32 v0, v0, v179
	global_store_short v[2:3], v0, off offset:192
	v_mul_f32_e32 v0, v8, v74
	v_cvt_pk_bf16_f32 v4, v0, v179
	v_add_co_u32_e32 v0, vcc, s0, v64
	s_mov_b32 s0, 0x11000
	s_nop 0
	v_addc_co_u32_e32 v1, vcc, 0, v65, vcc
	v_add_co_u32_e32 v2, vcc, s0, v64
	s_mov_b32 s0, 0x12000
	s_nop 0
	v_addc_co_u32_e32 v3, vcc, 0, v65, vcc
	global_store_short v[2:3], v4, off offset:-4096
	v_mul_f32_e32 v4, v56, v74
	v_cvt_pk_bf16_f32 v4, v4, v179
	global_store_short v[0:1], v4, off offset:64
	v_mul_f32_e32 v4, v40, v74
	v_cvt_pk_bf16_f32 v4, v4, v179
	global_store_short v[0:1], v4, off offset:128
	v_mul_f32_e32 v4, v24, v74
	v_cvt_pk_bf16_f32 v4, v4, v179
	global_store_short v[0:1], v4, off offset:192
	v_mul_f32_e32 v0, v9, v83
	v_cvt_pk_bf16_f32 v0, v0, v179
	global_store_short v[2:3], v0, off
	v_mul_f32_e32 v0, v57, v83
	v_cvt_pk_bf16_f32 v0, v0, v179
	global_store_short v[2:3], v0, off offset:64
	v_mul_f32_e32 v0, v41, v83
	v_cvt_pk_bf16_f32 v0, v0, v179
	global_store_short v[2:3], v0, off offset:128
	v_mul_f32_e32 v0, v25, v83
	v_cvt_pk_bf16_f32 v0, v0, v179
	global_store_short v[2:3], v0, off offset:192
	v_mul_f32_e32 v0, v10, v84
	v_cvt_pk_bf16_f32 v4, v0, v179
	v_add_co_u32_e32 v0, vcc, s0, v64
	s_mov_b32 s0, 0x13000
	s_nop 0
	v_addc_co_u32_e32 v1, vcc, 0, v65, vcc
	v_add_co_u32_e32 v2, vcc, s0, v64
	v_rcp_f32_e32 v68, v68
	s_nop 0
	v_addc_co_u32_e32 v3, vcc, 0, v65, vcc
	global_store_short v[2:3], v4, off offset:-4096
	v_mul_f32_e32 v4, v58, v84
	v_cvt_pk_bf16_f32 v4, v4, v179
	global_store_short v[0:1], v4, off offset:64
	v_mul_f32_e32 v4, v42, v84
	v_cvt_pk_bf16_f32 v4, v4, v179
	global_store_short v[0:1], v4, off offset:128
	v_mul_f32_e32 v4, v26, v84
	v_cvt_pk_bf16_f32 v4, v4, v179
	global_store_short v[0:1], v4, off offset:192
	v_mul_f32_e32 v0, v11, v85
	v_cvt_pk_bf16_f32 v0, v0, v179
	global_store_short v[2:3], v0, off
	v_mul_f32_e32 v0, v59, v85
	v_cvt_pk_bf16_f32 v0, v0, v179
	global_store_short v[2:3], v0, off offset:64
	v_mul_f32_e32 v0, v43, v85
	v_cvt_pk_bf16_f32 v0, v0, v179
	global_store_short v[2:3], v0, off offset:128
	v_mul_f32_e32 v0, v27, v85
	v_cvt_pk_bf16_f32 v0, v0, v179
	global_store_short v[2:3], v0, off offset:192
	v_mul_f32_e32 v0, v12, v68
	s_mov_b32 s0, 0x18000
	v_cvt_pk_bf16_f32 v4, v0, v179
	v_add_co_u32_e32 v0, vcc, s0, v64
	s_mov_b32 s0, 0x19000
	s_nop 0
	v_addc_co_u32_e32 v1, vcc, 0, v65, vcc
	v_add_co_u32_e32 v2, vcc, s0, v64
	v_rcp_f32_e32 v69, v69
	s_nop 0
	v_addc_co_u32_e32 v3, vcc, 0, v65, vcc
	global_store_short v[2:3], v4, off offset:-4096
	v_mul_f32_e32 v4, v60, v68
	v_cvt_pk_bf16_f32 v4, v4, v179
	global_store_short v[0:1], v4, off offset:64
	v_mul_f32_e32 v4, v44, v68
	v_cvt_pk_bf16_f32 v4, v4, v179
	global_store_short v[0:1], v4, off offset:128
	v_mul_f32_e32 v4, v28, v68
	v_cvt_pk_bf16_f32 v4, v4, v179
	global_store_short v[0:1], v4, off offset:192
	v_mul_f32_e32 v0, v13, v69
	v_cvt_pk_bf16_f32 v0, v0, v179
	global_store_short v[2:3], v0, off
	v_mul_f32_e32 v0, v61, v69
	v_cvt_pk_bf16_f32 v0, v0, v179
	v_rcp_f32_e32 v70, v70
	global_store_short v[2:3], v0, off offset:64
	v_mul_f32_e32 v0, v45, v69
	v_cvt_pk_bf16_f32 v0, v0, v179
	global_store_short v[2:3], v0, off offset:128
	v_mul_f32_e32 v0, v29, v69
	v_cvt_pk_bf16_f32 v0, v0, v179
	global_store_short v[2:3], v0, off offset:192
	v_mul_f32_e32 v0, v14, v70
	s_mov_b32 s0, 0x1a000
	v_cvt_pk_bf16_f32 v4, v0, v179
	v_add_co_u32_e32 v0, vcc, s0, v64
	s_mov_b32 s0, 0x1b000
	s_nop 0
	v_addc_co_u32_e32 v1, vcc, 0, v65, vcc
	v_add_co_u32_e32 v2, vcc, s0, v64
	v_rcp_f32_e32 v71, v71
	s_nop 0
	v_addc_co_u32_e32 v3, vcc, 0, v65, vcc
	global_store_short v[2:3], v4, off offset:-4096
	v_mul_f32_e32 v4, v62, v70
	v_cvt_pk_bf16_f32 v4, v4, v179
	global_store_short v[0:1], v4, off offset:64
	v_mul_f32_e32 v4, v46, v70
	v_cvt_pk_bf16_f32 v4, v4, v179
	global_store_short v[0:1], v4, off offset:128
	v_mul_f32_e32 v4, v30, v70
	v_cvt_pk_bf16_f32 v4, v4, v179
	global_store_short v[0:1], v4, off offset:192
	v_mul_f32_e32 v0, v15, v71
	v_cvt_pk_bf16_f32 v0, v0, v179
	global_store_short v[2:3], v0, off
	v_mul_f32_e32 v0, v63, v71
	v_cvt_pk_bf16_f32 v0, v0, v179
	global_store_short v[2:3], v0, off offset:64
	v_mul_f32_e32 v0, v47, v71
	v_cvt_pk_bf16_f32 v0, v0, v179
	global_store_short v[2:3], v0, off offset:128
	v_mul_f32_e32 v0, v31, v71
	v_cvt_pk_bf16_f32 v0, v0, v179
	global_store_short v[2:3], v0, off offset:192

; template <int D0> __device__ __forceinline__ void pv_one(f32x16& od, int vb, bf16x8 pa0, bf16x8 pa1, bf16x8 pa2, bf16x8 pa3) {
;     const s16x4 l0 = tr_read<v_rd_off(D0, 0, 0)>(vb), h0 = tr_read<v_rd_off(D0, 0, 1)>(vb), l1 = tr_read<v_rd_off(D0, 1, 0)>(vb), h1 = tr_read<v_rd_off(D0, 1, 1)>(vb);
;     const s16x4 l2 = tr_read<v_rd_off(D0, 2, 0)>(vb), h2 = tr_read<v_rd_off(D0, 2, 1)>(vb), l3 = tr_read<v_rd_off(D0, 3, 0)>(vb), h3 = tr_read<v_rd_off(D0, 3, 1)>(vb);
;     asm volatile("s_waitcnt lgkmcnt(0)" ::: "memory"); SBAR();
;     ...
;     od = __builtin_amdgcn_mfma_f32_32x32x16_bf16(pa0, PK(l0, h0), od, 0, 0, 0);
;     od = __builtin_amdgcn_mfma_f32_32x32x16_bf16(pa1, PK(l1, h1), od, 0, 0, 0);
;     od = __builtin_amdgcn_mfma_f32_32x32x16_bf16(pa2, PK(l2, h2), od, 0, 0, 0);
;     od = __builtin_amdgcn_mfma_f32_32x32x16_bf16(pa3, PK(l3, h3), od, 0, 0, 0);
;     ...
; }
; __device__ __forceinline__ void pv_d0(f32x16* o, int vb, bf16x8 pa0, bf16x8 pa1, bf16x8 pa2, bf16x8 pa3) {
;     pv_one<0>(o[0], vb, pa0, pa1, pa2, pa3); pv_one<1>(o[1], vb, pa0, pa1, pa2, pa3); pv_one<2>(o[2], vb, pa0, pa1, pa2, pa3); pv_one<3>(o[3], vb, pa0, pa1, pa2, pa3);
; }
; __device__ __forceinline__ void partialSM(f32x16& p0, f32x16& p1, float& m_reg, float& mn, float& alpha, const float C, const float thr_raw) {
;     float pmax = p0[0];
; #pragma unroll
;     for (int r = 1; r < 16; ++r) pmax = fmaxf(pmax, p0[r]);
; #pragma unroll
;     for (int r = 0; r < 16; ++r) pmax = fmaxf(pmax, p1[r]);
;     { auto rr = __builtin_amdgcn_permlane32_swap(__float_as_uint(pmax), __float_as_uint(pmax), false, false);
;       pmax = fmaxf(__uint_as_float(rr[0]), __uint_as_float(rr[1])); }
;     if (__builtin_expect(__all(pmax - m_reg <= thr_raw), 1)) { mn = m_reg; alpha = 1.f; }
;     else { mn = fmaxf(m_reg, pmax); alpha = __builtin_amdgcn_exp2f((m_reg - mn) * C); m_reg = mn; }
;     const float mnC = -mn * C;
; #pragma unroll
;     for (int r = 0; r < 16; ++r) p0[r] = fmaf(p0[r], C, mnC);
; #pragma unroll
;     for (int r = 0; r < 16; ++r) p1[r] = fmaf(p1[r], C, mnC);
; #pragma unroll
;     for (int r = 0; r < 16; ++r) p0[r] = __builtin_amdgcn_exp2f(p0[r]);
; }
; __device__ __forceinline__ void finishSM(f32x16& p0, f32x16& p1, float alpha, float& l_reg, bf16x8& pa0, bf16x8& pa1, bf16x8& pa2, bf16x8& pa3) {
; #pragma unroll
;     for (int r = 0; r < 16; ++r) p1[r] = __builtin_amdgcn_exp2f(p1[r]);
.LBB0_3487:
	v_cndmask_b32_e64 v168, v174, v168, s[46:47]
	v_mul_f32_e32 v174, 0xbdd53b94, v168
	v_fmamk_f32 v80, v80, 0x3dd53b94, v174
	v_fmamk_f32 v81, v81, 0x3dd53b94, v174
	v_fmamk_f32 v82, v82, 0x3dd53b94, v174
	v_fmamk_f32 v83, v83, 0x3dd53b94, v174
	v_fmamk_f32 v84, v84, 0x3dd53b94, v174
	v_fmamk_f32 v85, v85, 0x3dd53b94, v174
	v_fmamk_f32 v86, v86, 0x3dd53b94, v174
	v_fmamk_f32 v87, v87, 0x3dd53b94, v174
	v_fmamk_f32 v88, v88, 0x3dd53b94, v174
	v_fmamk_f32 v89, v89, 0x3dd53b94, v174
	v_fmamk_f32 v90, v90, 0x3dd53b94, v174
	v_fmamk_f32 v91, v91, 0x3dd53b94, v174
	v_fmamk_f32 v92, v92, 0x3dd53b94, v174
	v_fmamk_f32 v93, v93, 0x3dd53b94, v174
	v_fmamk_f32 v94, v94, 0x3dd53b94, v174
	v_fmamk_f32 v95, v95, 0x3dd53b94, v174
	v_fmamk_f32 v64, v64, 0x3dd53b94, v174
	v_fmamk_f32 v65, v65, 0x3dd53b94, v174
	v_fmamk_f32 v66, v66, 0x3dd53b94, v174
	v_fmamk_f32 v67, v67, 0x3dd53b94, v174
	v_fmamk_f32 v68, v68, 0x3dd53b94, v174
	v_fmamk_f32 v69, v69, 0x3dd53b94, v174
	v_fmamk_f32 v70, v70, 0x3dd53b94, v174
	v_fmamk_f32 v71, v71, 0x3dd53b94, v174
	v_fmamk_f32 v72, v72, 0x3dd53b94, v174
	v_fmamk_f32 v73, v73, 0x3dd53b94, v174
	v_fmamk_f32 v74, v74, 0x3dd53b94, v174
	v_fmamk_f32 v75, v75, 0x3dd53b94, v174
	v_fmamk_f32 v76, v76, 0x3dd53b94, v174
	v_fmamk_f32 v77, v77, 0x3dd53b94, v174
	v_fmamk_f32 v78, v78, 0x3dd53b94, v174
	v_fmac_f32_e32 v174, 0x3dd53b94, v79
	v_exp_f32_e32 v79, v80
	v_exp_f32_e32 v80, v81
	v_exp_f32_e32 v81, v82
	v_exp_f32_e32 v82, v83
	v_exp_f32_e32 v83, v84
	v_exp_f32_e32 v84, v85
	v_exp_f32_e32 v85, v86
	v_exp_f32_e32 v86, v87
	v_exp_f32_e32 v87, v88
	v_exp_f32_e32 v88, v89
	v_exp_f32_e32 v89, v90
	v_exp_f32_e32 v90, v91
	v_exp_f32_e32 v91, v92
	v_exp_f32_e32 v92, v93
	v_exp_f32_e32 v93, v94
	v_exp_f32_e32 v94, v95
	v_exp_f32_e32 v95, v64
	v_add_f32_e32 v64, 0, v79
	v_add_f32_e32 v64, v80, v64
	v_add_f32_e32 v64, v81, v64
	v_add_f32_e32 v64, v82, v64
	v_add_f32_e32 v64, v83, v64
	v_add_f32_e32 v64, v84, v64
	v_add_f32_e32 v64, v85, v64
	v_add_f32_e32 v64, v86, v64
	v_add_f32_e32 v64, v87, v64
	v_add_f32_e32 v64, v88, v64
	v_add_f32_e32 v64, v89, v64
	v_add_f32_e32 v64, v90, v64
	v_add_f32_e32 v64, v91, v64
	v_exp_f32_e32 v207, v65
	v_add_f32_e32 v64, v92, v64
	v_exp_f32_e32 v208, v66
	v_add_f32_e32 v64, v93, v64
	v_exp_f32_e32 v209, v67
	v_add_f32_e32 v64, v94, v64
	v_exp_f32_e32 v210, v68
	v_add_f32_e32 v64, v95, v64
	v_exp_f32_e32 v211, v69
	v_add_f32_e32 v64, v207, v64
	v_exp_f32_e32 v220, v70
	v_add_f32_e32 v64, v208, v64
	v_exp_f32_e32 v221, v71
	v_add_f32_e32 v64, v209, v64
	v_exp_f32_e32 v222, v72
	v_add_f32_e32 v64, v210, v64
	v_exp_f32_e32 v223, v73
	v_add_f32_e32 v64, v211, v64
	v_exp_f32_e32 v227, v74
	v_add_f32_e32 v64, v220, v64
	v_exp_f32_e32 v228, v75
	v_add_f32_e32 v64, v221, v64
	v_exp_f32_e32 v229, v76
	v_add_f32_e32 v64, v222, v64
	v_exp_f32_e32 v230, v77
	v_add_f32_e32 v64, v223, v64
	v_exp_f32_e32 v231, v78
	v_add_f32_e32 v64, v227, v64
	v_exp_f32_e32 v232, v174
	v_add_f32_e32 v64, v228, v64
	v_add_f32_e32 v64, v229, v64
	v_add_f32_e32 v64, v230, v64
	v_add_f32_e32 v64, v231, v64
	v_add_f32_e32 v64, v232, v64
	v_mov_b32_e32 v65, v64
	s_nop 1
	v_permlane32_swap_b32_e32 v64, v65
	v_add_f32_e32 v174, v64, v65
	s_add_i32 s7, s7, 1
	v_fmac_f32_e32 v174, v205, v206
	v_cvt_pk_bf16_f32 v64, v79, v80
	v_cvt_pk_bf16_f32 v65, v81, v82
	v_cvt_pk_bf16_f32 v66, v83, v84
	v_cvt_pk_bf16_f32 v67, v85, v86
	v_cvt_pk_bf16_f32 v68, v87, v88
	v_cvt_pk_bf16_f32 v69, v89, v90
	v_cvt_pk_bf16_f32 v70, v91, v92
	v_cvt_pk_bf16_f32 v71, v93, v94
	v_cvt_pk_bf16_f32 v72, v95, v207
	v_cvt_pk_bf16_f32 v73, v208, v209
	v_cvt_pk_bf16_f32 v74, v210, v211
	v_cvt_pk_bf16_f32 v75, v220, v221
	v_cvt_pk_bf16_f32 v76, v222, v223
	v_cvt_pk_bf16_f32 v77, v227, v228
	v_cvt_pk_bf16_f32 v78, v229, v230
	v_cvt_pk_bf16_f32 v79, v231, v232
	s_nop 0
	v_permlane32_swap_b32_e32 v64, v66
	v_permlane32_swap_b32_e32 v65, v67
	v_permlane32_swap_b32_e32 v68, v70
	v_permlane32_swap_b32_e32 v69, v71
	v_permlane32_swap_b32_e32 v72, v74
	v_permlane32_swap_b32_e32 v73, v75
	v_permlane32_swap_b32_e32 v76, v78
	v_permlane32_swap_b32_e32 v77, v79
	v_add_u32_e32 v205, s23, v167
	ds_read_b64_tr_b16 v[80:81], v205 offset:0
	ds_read_b64_tr_b16 v[82:83], v205 offset:0x800
	ds_read_b64_tr_b16 v[84:85], v205 offset:0x1000
	ds_read_b64_tr_b16 v[86:87], v205 offset:0x1800
	ds_read_b64_tr_b16 v[88:89], v205 offset:0x2000
	ds_read_b64_tr_b16 v[90:91], v205 offset:0x2800
	ds_read_b64_tr_b16 v[92:93], v205 offset:0x3000
	ds_read_b64_tr_b16 v[94:95], v205 offset:0x3800
	s_nop 0
	s_waitcnt lgkmcnt(6)
	v_mfma_f32_32x32x16_bf16 v[0:15], v[64:67], v[80:83], v[0:15]
	ds_read_b64_tr_b16 v[80:81], v205 offset:0x200
	ds_read_b64_tr_b16 v[82:83], v205 offset:0xa00
	s_waitcnt lgkmcnt(6)
	v_mfma_f32_32x32x16_bf16 v[0:15], v[68:71], v[84:87], v[0:15]
	ds_read_b64_tr_b16 v[84:85], v205 offset:0x1200
	ds_read_b64_tr_b16 v[86:87], v205 offset:0x1a00
	s_waitcnt lgkmcnt(6)
	v_mfma_f32_32x32x16_bf16 v[0:15], v[72:75], v[88:91], v[0:15]
	ds_read_b64_tr_b16 v[88:89], v205 offset:0x2200
	ds_read_b64_tr_b16 v[90:91], v205 offset:0x2a00
	s_waitcnt lgkmcnt(6)
	v_mfma_f32_32x32x16_bf16 v[0:15], v[76:79], v[92:95], v[0:15]
	ds_read_b64_tr_b16 v[92:93], v205 offset:0x3200
	ds_read_b64_tr_b16 v[94:95], v205 offset:0x3a00
	s_waitcnt lgkmcnt(6)
	v_mfma_f32_32x32x16_bf16 v[48:63], v[64:67], v[80:83], v[48:63]
	ds_read_b64_tr_b16 v[80:81], v205 offset:0x400
	ds_read_b64_tr_b16 v[82:83], v205 offset:0xc00
	s_waitcnt lgkmcnt(6)
	v_mfma_f32_32x32x16_bf16 v[48:63], v[68:71], v[84:87], v[48:63]
	ds_read_b64_tr_b16 v[84:85], v205 offset:0x1400
	ds_read_b64_tr_b16 v[86:87], v205 offset:0x1c00
	s_waitcnt lgkmcnt(6)
	v_mfma_f32_32x32x16_bf16 v[48:63], v[72:75], v[88:91], v[48:63]
	ds_read_b64_tr_b16 v[88:89], v205 offset:0x2400
	ds_read_b64_tr_b16 v[90:91], v205 offset:0x2c00
	s_waitcnt lgkmcnt(6)
	v_mfma_f32_32x32x16_bf16 v[48:63], v[76:79], v[92:95], v[48:63]
	ds_read_b64_tr_b16 v[92:93], v205 offset:0x3400
	ds_read_b64_tr_b16 v[94:95], v205 offset:0x3c00
	s_waitcnt lgkmcnt(6)
	v_mfma_f32_32x32x16_bf16 v[32:47], v[64:67], v[80:83], v[32:47]
	ds_read_b64_tr_b16 v[80:81], v205 offset:0x600
	ds_read_b64_tr_b16 v[82:83], v205 offset:0xe00
	s_waitcnt lgkmcnt(6)
	v_mfma_f32_32x32x16_bf16 v[32:47], v[68:71], v[84:87], v[32:47]
	ds_read_b64_tr_b16 v[84:85], v205 offset:0x1600
	ds_read_b64_tr_b16 v[86:87], v205 offset:0x1e00
	s_waitcnt lgkmcnt(6)
	v_mfma_f32_32x32x16_bf16 v[32:47], v[72:75], v[88:91], v[32:47]
	ds_read_b64_tr_b16 v[88:89], v205 offset:0x2600
	ds_read_b64_tr_b16 v[90:91], v205 offset:0x2e00
	s_waitcnt lgkmcnt(6)
	v_mfma_f32_32x32x16_bf16 v[32:47], v[76:79], v[92:95], v[32:47]
	ds_read_b64_tr_b16 v[92:93], v205 offset:0x3600
	ds_read_b64_tr_b16 v[94:95], v205 offset:0x3e00
	s_waitcnt lgkmcnt(6)
	v_mfma_f32_32x32x16_bf16 v[16:31], v[64:67], v[80:83], v[16:31]
	s_waitcnt vmcnt(0)
	s_add_i32 s22, s22, 64
	v_cmp_eq_u32_e32 vcc, s7, v204
	s_or_b64 s[48:49], vcc, s[48:49]
	v_mov_b32_e32 v205, v174
	s_waitcnt vmcnt(0)
	s_waitcnt lgkmcnt(0)
	s_barrier
; __device__ __forceinline__ int crow(int r, int hi) { return (r & 3) + 8 * (r >> 2) + 4 * hi; }
; #define SBAR() __builtin_amdgcn_sched_barrier(0)
; template <int D0> __device__ __forceinline__ void pv_one(f32x16& od, int vb, bf16x8 pa0, bf16x8 pa1, bf16x8 pa2, bf16x8 pa3) {
;     ...
;     od = __builtin_amdgcn_mfma_f32_32x32x16_bf16(pa0, PK(l0, h0), od, 0, 0, 0);
;     od = __builtin_amdgcn_mfma_f32_32x32x16_bf16(pa1, PK(l1, h1), od, 0, 0, 0);
;     od = __builtin_amdgcn_mfma_f32_32x32x16_bf16(pa2, PK(l2, h2), od, 0, 0, 0);
;     od = __builtin_amdgcn_mfma_f32_32x32x16_bf16(pa3, PK(l3, h3), od, 0, 0, 0);
; template <int DQK, int LDQ, int LDK, int LDV> ...
;     ...
;     for (int j = 0; j < NT; ++j) {
;         const int buf = j & 1;
;         if (j + 1 < NT) STAGE(buf ^ 1, (j + 1) * 64);
;         f32x16 p0, p1; float mn, al; bf16x8 pa0, pa1, pa2, pa3;
;         SBAR(); qkt<DQK>(p0, p1, K_lds + buf * SHM_K, qr, r32, hi);
;         partialSM(p0, p1, m_reg, mn, al, C, thr_raw);
;         if (__any(al < 1.f)) { if (hi == 0) al_l[r32] = al; asm volatile("s_waitcnt lgkmcnt(0)" ::: "memory");
; #pragma unroll
;             for (int d = 0; d < 4; ++d)
; #pragma unroll
;                 for (int r = 0; r < 16; ++r) o[d][r] *= al_l[crow(r, hi)]; }
;         finishSM(p0, p1, al, l_reg, pa0, pa1, pa2, pa3); SBAR();
;         pv_d0(o, vb0 + buf * SHM_V, pa0, pa1, pa2, pa3);
;         asm volatile("s_waitcnt vmcnt(0)" ::: "memory");
;         __syncthreads();
	s_waitcnt lgkmcnt(4)
	v_mfma_f32_32x32x16_bf16 v[16:31], v[68:71], v[84:87], v[16:31]
	s_waitcnt lgkmcnt(2)
	v_mfma_f32_32x32x16_bf16 v[16:31], v[72:75], v[88:91], v[16:31]
	s_waitcnt lgkmcnt(0)
	v_mfma_f32_32x32x16_bf16 v[16:31], v[76:79], v[92:95], v[16:31]
	s_andn2_b64 exec, exec, s[48:49]
	s_cbranch_execz .LBB0_3491

; template <int D0> __device__ __forceinline__ void pv_one(f32x16& od, int vb, bf16x8 pa0, bf16x8 pa1, bf16x8 pa2, bf16x8 pa3) {
;     const s16x4 l0 = tr_read<v_rd_off(D0, 0, 0)>(vb), h0 = tr_read<v_rd_off(D0, 0, 1)>(vb), l1 = tr_read<v_rd_off(D0, 1, 0)>(vb), h1 = tr_read<v_rd_off(D0, 1, 1)>(vb);
;     const s16x4 l2 = tr_read<v_rd_off(D0, 2, 0)>(vb), h2 = tr_read<v_rd_off(D0, 2, 1)>(vb), l3 = tr_read<v_rd_off(D0, 3, 0)>(vb), h3 = tr_read<v_rd_off(D0, 3, 1)>(vb);
;     asm volatile("s_waitcnt lgkmcnt(0)" ::: "memory"); SBAR();
;     ...
;     od = __builtin_amdgcn_mfma_f32_32x32x16_bf16(pa0, PK(l0, h0), od, 0, 0, 0);
;     od = __builtin_amdgcn_mfma_f32_32x32x16_bf16(pa1, PK(l1, h1), od, 0, 0, 0);
;     od = __builtin_amdgcn_mfma_f32_32x32x16_bf16(pa2, PK(l2, h2), od, 0, 0, 0);
;     od = __builtin_amdgcn_mfma_f32_32x32x16_bf16(pa3, PK(l3, h3), od, 0, 0, 0);
;     ...
; }
; __device__ __forceinline__ void pv_d0(f32x16* o, int vb, bf16x8 pa0, bf16x8 pa1, bf16x8 pa2, bf16x8 pa3) {
;     pv_one<0>(o[0], vb, pa0, pa1, pa2, pa3); pv_one<1>(o[1], vb, pa0, pa1, pa2, pa3); pv_one<2>(o[2], vb, pa0, pa1, pa2, pa3); pv_one<3>(o[3], vb, pa0, pa1, pa2, pa3);
; }
; __device__ __forceinline__ void partialSM(f32x16& p0, f32x16& p1, float& m_reg, float& mn, float& alpha, const float C, const float thr_raw) {
;     float pmax = p0[0];
; #pragma unroll
;     for (int r = 1; r < 16; ++r) pmax = fmaxf(pmax, p0[r]);
; #pragma unroll
;     for (int r = 0; r < 16; ++r) pmax = fmaxf(pmax, p1[r]);
;     { auto rr = __builtin_amdgcn_permlane32_swap(__float_as_uint(pmax), __float_as_uint(pmax), false, false);
;       pmax = fmaxf(__uint_as_float(rr[0]), __uint_as_float(rr[1])); }
;     if (__builtin_expect(__all(pmax - m_reg <= thr_raw), 1)) { mn = m_reg; alpha = 1.f; }
;     else { mn = fmaxf(m_reg, pmax); alpha = __builtin_amdgcn_exp2f((m_reg - mn) * C); m_reg = mn; }
;     const float mnC = -mn * C;
; #pragma unroll
;     for (int r = 0; r < 16; ++r) p0[r] = fmaf(p0[r], C, mnC);
; #pragma unroll
;     for (int r = 0; r < 16; ++r) p1[r] = fmaf(p1[r], C, mnC);
; #pragma unroll
;     for (int r = 0; r < 16; ++r) p0[r] = __builtin_amdgcn_exp2f(p0[r]);
; }
; __device__ __forceinline__ void finishSM(f32x16& p0, f32x16& p1, float alpha, float& l_reg, bf16x8& pa0, bf16x8& pa1, bf16x8& pa2, bf16x8& pa3) {
; #pragma unroll
;     for (int r = 0; r < 16; ++r) p1[r] = __builtin_amdgcn_exp2f(p1[r]);
.LBB0_3495:
	v_cndmask_b32_e64 v97, v97, v168, s[40:41]
	v_mul_f32_e32 v97, 0xbdd53b94, v97
	v_fmamk_f32 v80, v80, 0x3dd53b94, v97
	v_fmamk_f32 v81, v81, 0x3dd53b94, v97
	v_fmamk_f32 v82, v82, 0x3dd53b94, v97
	v_fmamk_f32 v83, v83, 0x3dd53b94, v97
	v_fmamk_f32 v84, v84, 0x3dd53b94, v97
	v_fmamk_f32 v85, v85, 0x3dd53b94, v97
	v_fmamk_f32 v86, v86, 0x3dd53b94, v97
	v_fmamk_f32 v87, v87, 0x3dd53b94, v97
	v_fmamk_f32 v88, v88, 0x3dd53b94, v97
	v_fmamk_f32 v89, v89, 0x3dd53b94, v97
	v_fmamk_f32 v90, v90, 0x3dd53b94, v97
	v_fmamk_f32 v91, v91, 0x3dd53b94, v97
	v_fmamk_f32 v92, v92, 0x3dd53b94, v97
	v_fmamk_f32 v93, v93, 0x3dd53b94, v97
	v_fmamk_f32 v94, v94, 0x3dd53b94, v97
	v_fmamk_f32 v95, v95, 0x3dd53b94, v97
	v_fmamk_f32 v64, v64, 0x3dd53b94, v97
	v_fmamk_f32 v65, v65, 0x3dd53b94, v97
	v_fmamk_f32 v66, v66, 0x3dd53b94, v97
	v_fmamk_f32 v67, v67, 0x3dd53b94, v97
	v_fmamk_f32 v68, v68, 0x3dd53b94, v97
	v_fmamk_f32 v69, v69, 0x3dd53b94, v97
	v_fmamk_f32 v70, v70, 0x3dd53b94, v97
	v_fmamk_f32 v71, v71, 0x3dd53b94, v97
	v_fmamk_f32 v72, v72, 0x3dd53b94, v97
	v_fmamk_f32 v73, v73, 0x3dd53b94, v97
	v_fmamk_f32 v74, v74, 0x3dd53b94, v97
	v_fmamk_f32 v75, v75, 0x3dd53b94, v97
	v_fmamk_f32 v76, v76, 0x3dd53b94, v97
	v_fmamk_f32 v77, v77, 0x3dd53b94, v97
	v_fmamk_f32 v78, v78, 0x3dd53b94, v97
	v_fmac_f32_e32 v97, 0x3dd53b94, v79
	v_exp_f32_e32 v79, v80
	v_exp_f32_e32 v80, v81
	v_exp_f32_e32 v81, v82
	v_exp_f32_e32 v82, v83
	v_exp_f32_e32 v83, v84
	v_exp_f32_e32 v84, v85
	v_exp_f32_e32 v85, v86
	v_exp_f32_e32 v86, v87
	v_exp_f32_e32 v87, v88
	v_exp_f32_e32 v88, v89
	v_exp_f32_e32 v89, v90
	v_exp_f32_e32 v90, v91
	v_exp_f32_e32 v91, v92
	v_exp_f32_e32 v92, v93
	v_exp_f32_e32 v93, v94
	v_exp_f32_e32 v94, v95
	v_exp_f32_e32 v95, v64
	v_add_f32_e32 v64, 0, v79
	v_add_f32_e32 v64, v80, v64
	v_add_f32_e32 v64, v81, v64
	v_add_f32_e32 v64, v82, v64
	v_add_f32_e32 v64, v83, v64
	v_add_f32_e32 v64, v84, v64
	v_add_f32_e32 v64, v85, v64
	v_add_f32_e32 v64, v86, v64
	v_add_f32_e32 v64, v87, v64
	v_add_f32_e32 v64, v88, v64
	v_add_f32_e32 v64, v89, v64
	v_add_f32_e32 v64, v90, v64
	v_add_f32_e32 v64, v91, v64
	v_exp_f32_e32 v98, v65
	v_add_f32_e32 v64, v92, v64
	v_exp_f32_e32 v99, v66
	v_add_f32_e32 v64, v93, v64
	v_exp_f32_e32 v100, v67
	v_add_f32_e32 v64, v94, v64
	v_exp_f32_e32 v101, v68
	v_add_f32_e32 v64, v95, v64
	v_exp_f32_e32 v102, v69
	v_add_f32_e32 v64, v98, v64
	v_exp_f32_e32 v103, v70
	v_add_f32_e32 v64, v99, v64
	v_exp_f32_e32 v104, v71
	v_add_f32_e32 v64, v100, v64
	v_exp_f32_e32 v105, v72
	v_add_f32_e32 v64, v101, v64
	v_exp_f32_e32 v106, v73
	v_add_f32_e32 v64, v102, v64
	v_exp_f32_e32 v107, v74
	v_add_f32_e32 v64, v103, v64
	v_exp_f32_e32 v108, v75
	v_add_f32_e32 v64, v104, v64
	v_exp_f32_e32 v109, v76
	v_add_f32_e32 v64, v105, v64
	v_exp_f32_e32 v110, v77
	v_add_f32_e32 v64, v106, v64
	v_exp_f32_e32 v111, v78
	v_add_f32_e32 v64, v107, v64
	v_exp_f32_e32 v97, v97
	v_add_f32_e32 v64, v108, v64
	v_add_f32_e32 v64, v109, v64
	v_add_f32_e32 v64, v110, v64
	v_add_f32_e32 v64, v111, v64
	v_add_f32_e32 v64, v97, v64
	v_mov_b32_e32 v65, v64
	s_nop 1
	v_permlane32_swap_b32_e32 v64, v65
	v_cvt_pk_bf16_f32 v66, v79, v80
	v_cvt_pk_bf16_f32 v67, v81, v82
	v_cvt_pk_bf16_f32 v68, v83, v84
	v_cvt_pk_bf16_f32 v69, v85, v86
	v_cvt_pk_bf16_f32 v70, v87, v88
	v_cvt_pk_bf16_f32 v71, v89, v90
	v_cvt_pk_bf16_f32 v72, v91, v92
	v_cvt_pk_bf16_f32 v73, v93, v94
	v_cvt_pk_bf16_f32 v74, v95, v98
	v_cvt_pk_bf16_f32 v75, v99, v100
	v_cvt_pk_bf16_f32 v76, v101, v102
	v_cvt_pk_bf16_f32 v77, v103, v104
	v_cvt_pk_bf16_f32 v78, v105, v106
	v_cvt_pk_bf16_f32 v79, v107, v108
	v_cvt_pk_bf16_f32 v80, v109, v110
	v_cvt_pk_bf16_f32 v81, v111, v97
	s_nop 0
	v_permlane32_swap_b32_e32 v66, v68
	v_permlane32_swap_b32_e32 v67, v69
	v_permlane32_swap_b32_e32 v70, v72
	v_permlane32_swap_b32_e32 v71, v73
	v_permlane32_swap_b32_e32 v74, v76
	v_permlane32_swap_b32_e32 v75, v77
	v_permlane32_swap_b32_e32 v78, v80
	v_permlane32_swap_b32_e32 v79, v81
	v_lshl_add_u32 v94, v148, 14, v167
	ds_read_b64_tr_b16 v[82:83], v94 offset:0
	ds_read_b64_tr_b16 v[84:85], v94 offset:0x800
	ds_read_b64_tr_b16 v[86:87], v94 offset:0x1000
	ds_read_b64_tr_b16 v[88:89], v94 offset:0x1800
	ds_read_b64_tr_b16 v[90:91], v94 offset:0x2000
	ds_read_b64_tr_b16 v[92:93], v94 offset:0x2800
	ds_read_b64_tr_b16 v[98:99], v94 offset:0x3000
	ds_read_b64_tr_b16 v[100:101], v94 offset:0x3800
	s_nop 0
	s_waitcnt lgkmcnt(6)
	v_mfma_f32_32x32x16_bf16 v[0:15], v[66:69], v[82:85], v[0:15]
	ds_read_b64_tr_b16 v[82:83], v94 offset:0x200
	ds_read_b64_tr_b16 v[84:85], v94 offset:0xa00
	s_waitcnt lgkmcnt(6)
	v_mfma_f32_32x32x16_bf16 v[0:15], v[70:73], v[86:89], v[0:15]
	ds_read_b64_tr_b16 v[86:87], v94 offset:0x1200
	ds_read_b64_tr_b16 v[88:89], v94 offset:0x1a00
	s_waitcnt lgkmcnt(6)
	v_mfma_f32_32x32x16_bf16 v[0:15], v[74:77], v[90:93], v[0:15]
	ds_read_b64_tr_b16 v[90:91], v94 offset:0x2200
	ds_read_b64_tr_b16 v[92:93], v94 offset:0x2a00
	s_waitcnt lgkmcnt(6)
	v_mfma_f32_32x32x16_bf16 v[0:15], v[78:81], v[98:101], v[0:15]
	ds_read_b64_tr_b16 v[98:99], v94 offset:0x3200
	ds_read_b64_tr_b16 v[100:101], v94 offset:0x3a00
	s_waitcnt lgkmcnt(6)
	v_mfma_f32_32x32x16_bf16 v[48:63], v[66:69], v[82:85], v[48:63]
	ds_read_b64_tr_b16 v[82:83], v94 offset:0x400
	ds_read_b64_tr_b16 v[84:85], v94 offset:0xc00
	s_waitcnt lgkmcnt(6)
	v_mfma_f32_32x32x16_bf16 v[48:63], v[70:73], v[86:89], v[48:63]
	ds_read_b64_tr_b16 v[86:87], v94 offset:0x1400
	ds_read_b64_tr_b16 v[88:89], v94 offset:0x1c00
	s_waitcnt lgkmcnt(6)
	v_mfma_f32_32x32x16_bf16 v[48:63], v[74:77], v[90:93], v[48:63]
	ds_read_b64_tr_b16 v[90:91], v94 offset:0x2400
	ds_read_b64_tr_b16 v[92:93], v94 offset:0x2c00
	s_waitcnt lgkmcnt(6)
	v_mfma_f32_32x32x16_bf16 v[48:63], v[78:81], v[98:101], v[48:63]
	ds_read_b64_tr_b16 v[98:99], v94 offset:0x3400
	ds_read_b64_tr_b16 v[100:101], v94 offset:0x3c00
	s_waitcnt lgkmcnt(6)
	v_mfma_f32_32x32x16_bf16 v[32:47], v[66:69], v[82:85], v[32:47]
	ds_read_b64_tr_b16 v[82:83], v94 offset:0x600
	ds_read_b64_tr_b16 v[84:85], v94 offset:0xe00
	s_waitcnt lgkmcnt(6)
	v_mfma_f32_32x32x16_bf16 v[32:47], v[70:73], v[86:89], v[32:47]
	ds_read_b64_tr_b16 v[86:87], v94 offset:0x1600
	ds_read_b64_tr_b16 v[88:89], v94 offset:0x1e00
	s_waitcnt lgkmcnt(6)
	v_mfma_f32_32x32x16_bf16 v[32:47], v[74:77], v[90:93], v[32:47]
	ds_read_b64_tr_b16 v[90:91], v94 offset:0x2600
	ds_read_b64_tr_b16 v[92:93], v94 offset:0x2e00
	s_waitcnt lgkmcnt(6)
	v_mfma_f32_32x32x16_bf16 v[32:47], v[78:81], v[98:101], v[32:47]
	ds_read_b64_tr_b16 v[98:99], v94 offset:0x3600
	ds_read_b64_tr_b16 v[100:101], v94 offset:0x3e00
	s_waitcnt lgkmcnt(6)
	v_mfma_f32_32x32x16_bf16 v[16:31], v[66:69], v[82:85], v[16:31]
	s_waitcnt vmcnt(0)
	s_waitcnt lgkmcnt(0)
	s_barrier
; template <int D0> __device__ __forceinline__ void pv_one(f32x16& od, int vb, bf16x8 pa0, bf16x8 pa1, bf16x8 pa2, bf16x8 pa3) {
;     ...
;     od = __builtin_amdgcn_mfma_f32_32x32x16_bf16(pa0, PK(l0, h0), od, 0, 0, 0);
;     od = __builtin_amdgcn_mfma_f32_32x32x16_bf16(pa1, PK(l1, h1), od, 0, 0, 0);
;     od = __builtin_amdgcn_mfma_f32_32x32x16_bf16(pa2, PK(l2, h2), od, 0, 0, 0);
;     od = __builtin_amdgcn_mfma_f32_32x32x16_bf16(pa3, PK(l3, h3), od, 0, 0, 0);
; template <int DQK, int LDQ, int LDK, int LDV> ...
;     ...
;     if (hi == 0) li_l[r32] = l_reg; asm volatile("s_waitcnt lgkmcnt(0)" ::: "memory");
	s_waitcnt lgkmcnt(4)
	v_mfma_f32_32x32x16_bf16 v[16:31], v[70:73], v[86:89], v[16:31]
	s_waitcnt lgkmcnt(2)
	v_mfma_f32_32x32x16_bf16 v[16:31], v[74:77], v[90:93], v[16:31]
	s_waitcnt lgkmcnt(0)
	v_mfma_f32_32x32x16_bf16 v[16:31], v[78:81], v[98:101], v[16:31]
	s_and_saveexec_b64 s[40:41], s[38:39]
	s_cbranch_execz .LBB0_3388
	v_add_f32_e32 v64, v64, v65
	v_fmac_f32_e32 v64, v174, v96
	ds_write_b32 v147, v64
	s_branch .LBB0_3388
